# speedup vs baseline: 1.0345x; 1.0207x over previous
; #define LAS __attribute__((address_space(3)))
; __global__ void __launch_bounds__(512, 2) hymba_fwd(Params p) {
;     extern __shared__ __attribute__((aligned(16))) unsigned char lds_raw[];
;     LAS unsigned char* lds = (LAS unsigned char*)lds_raw;
;     cg::grid_group grid = cg::this_grid();
;     const int tid = threadIdx.x;
;     volatile LAS unsigned* bst = (volatile LAS unsigned*)(lds + LDS_BYTES - 64);
;     if (tid == 0) { bst[0] = 0u; bst[1] = 0u; }
;     __syncthreads();
;     if (blockIdx.x == 0) for (int i = tid; i < 4096; i += 512) ((unsigned*)(p.ws + WS_BAR))[i] = 0u;
.LBB0_2:
	s_or_b64 exec, exec, s[4:5]
	s_load_dwordx16 s[4:19], s[0:1], 0x0
	s_load_dwordx16 s[48:63], s[0:1], 0x40
	s_cmp_lg_u32 s2, 0
	s_waitcnt lgkmcnt(0)
	v_writelane_b32 v255, s62, 8
	v_writelane_b32 v255, s63, 9
	s_barrier
	v_writelane_b32 v253, s4, 2
	s_nop 1
	v_writelane_b32 v253, s5, 3
	v_writelane_b32 v253, s6, 4
	v_writelane_b32 v253, s7, 5
	v_writelane_b32 v253, s8, 6
	v_writelane_b32 v253, s9, 7
	v_writelane_b32 v253, s10, 8
	v_writelane_b32 v253, s11, 9
	v_writelane_b32 v253, s12, 10
	v_writelane_b32 v253, s13, 11
	v_writelane_b32 v253, s14, 12
	v_writelane_b32 v253, s15, 13
	v_writelane_b32 v253, s16, 14
	v_writelane_b32 v253, s17, 15
	v_writelane_b32 v253, s18, 16
	v_writelane_b32 v253, s19, 17
	s_cbranch_scc1 .LBB0_12
	s_add_u32 s6, s92, 0x1b397000
	v_lshlrev_b32_e32 v2, 2, v201
	s_addc_u32 s7, s93, 0
	v_lshrrev_b32_e32 v1, 9, v201
	v_mov_b32_e32 v3, 0
	v_add_u32_e32 v4, 0x800, v2
	v_xor_b32_e32 v1, 7, v1
	global_store_dword v2, v3, s[6:7]
	global_store_dword v4, v3, s[6:7]
	v_or_b32_e32 v4, 0x1000, v2
	v_add_u32_e32 v2, 0x1800, v2
	global_store_dword v4, v3, s[6:7]
	global_store_dword v2, v3, s[6:7]
	v_add_u32_e32 v2, 0xa00, v201
	v_or_b32_e32 v4, 0x800, v201
	v_cmp_lt_u32_e32 vcc, 4, v1
	v_cmp_lt_u32_e64 s[4:5], 3, v1
	s_and_saveexec_b64 s[8:9], s[4:5]
	s_cbranch_execz .LBB0_5
	v_lshlrev_b32_e32 v4, 2, v4
	global_store_dword v4, v3, s[6:7]

; __device__ __forceinline__ void p0_prologue(const Params& p, LAS unsigned char* lds, int tid) {
;     ...
;     for (int it = gw; it < I_LAYER * DEPTH; it += NGW) {
;         const int l = it / I_LAYER; int r = it % I_LAYER;
;         unsigned char* wl = p.ws + (size_t)l * LAYER_BYTES;
;         if (r < I_IN) { p0_transpose_item(p.in[3] + (size_t)l * DM * INW, DM, INW, p.in[2] + l * DM, nullptr, (bf16_t*)(wl + LO_WIN), scr, r, lane); continue; } r -= I_IN;
;         if (r < I_UP) { p0_transpose_item(p.in[21] + (size_t)l * DM * DFF, DM, DFF, p.in[20] + l * DM, nullptr, (bf16_t*)(wl + LO_WUP), scr, r, lane); continue; } r -= I_UP;
;         if (r < I_DN) { p0_transpose_item(p.in[22] + (size_t)l * DFF * DM, DFF, DM, nullptr, nullptr, (bf16_t*)(wl + LO_WDN), scr, r, lane); continue; } r -= I_DN;
;         if (r < I_GLU) { p0_transpose_item(p.in[15] + (size_t)l * 1024 * 1024, 1024, 1024, nullptr, nullptr, (bf16_t*)(wl + LO_WGLU), scr, r, lane); continue; } r -= I_GLU;
;         p0_transpose_item(p.in[19] + (size_t)l * DM * DM, DM, DM, p.in[17] + l * 1024, p.in[18] + l * 1024, (bf16_t*)(wl + LO_WOUT), scr, r, lane);
;     }
.LBB0_114:
	v_writelane_b32 v253, s2, 34
	s_or_b64 exec, exec, s[12:13]
	s_mov_b32 s0, 0x2a00
	v_cmp_gt_i32_e32 vcc, s0, v66
	s_and_saveexec_b64 s[4:5], vcc
	s_cbranch_execz .LBB0_181
	v_lshl_add_u32 v3, v11, 13, 0
	v_lshrrev_b32_e32 v4, 4, v10
	v_lshlrev_b32_e32 v7, 4, v201
	v_lshl_add_u32 v6, v4, 2, v3
	v_and_b32_e32 v7, 0x70, v7
	s_movk_i32 s1, 0x50
	v_lshlrev_b32_e32 v5, 2, v10
	s_movk_i32 s0, 0x70
	v_xad_u32 v91, v7, s1, v6
	s_movk_i32 s1, 0x60
	v_lshrrev_b32_e32 v94, 3, v10
	v_add_u32_e32 v71, v6, v7
	v_xad_u32 v87, v7, 16, v6
	v_xad_u32 v88, v7, 32, v6
	v_xad_u32 v89, v7, 48, v6
	v_xad_u32 v90, v7, 64, v6
	v_xad_u32 v92, v7, s1, v6
	v_xad_u32 v93, v7, s0, v6
	v_bitop3_b32 v7, v94, 28, v5 bitop3:0x48
	v_or_b32_e32 v96, 8, v94
	v_lshlrev_b32_e32 v6, 7, v94
	v_lshlrev_b32_e32 v7, 2, v7
	v_bitop3_b32 v8, v96, 28, v5 bitop3:0x48
	v_add3_u32 v95, v3, v6, v7
	v_lshlrev_b32_e32 v6, 7, v96
	v_lshlrev_b32_e32 v8, 2, v8
	v_or_b32_e32 v98, 16, v94
	v_add3_u32 v97, v3, v6, v8
	v_bitop3_b32 v8, v98, 28, v5 bitop3:0x48
	v_lshlrev_b32_e32 v6, 7, v98
	v_lshlrev_b32_e32 v8, 2, v8
	v_or_b32_e32 v100, 24, v94
	v_add3_u32 v99, v3, v6, v8
	v_bitop3_b32 v8, v100, 28, v5 bitop3:0x48
	v_lshlrev_b32_e32 v6, 7, v100
	v_lshlrev_b32_e32 v8, 2, v8
	v_or_b32_e32 v102, 32, v94
	v_add3_u32 v101, v3, v6, v8
	v_lshlrev_b32_e32 v6, 7, v102
	v_or_b32_e32 v104, 40, v94
	v_add3_u32 v103, v3, v6, v7
	v_bitop3_b32 v7, v104, 28, v5 bitop3:0x48
	v_readlane_b32 s36, v253, 18
	v_lshlrev_b32_e32 v6, 7, v104
	v_lshlrev_b32_e32 v7, 2, v7
	v_or_b32_e32 v106, 48, v94
	v_readlane_b32 s40, v253, 22
	v_readlane_b32 s41, v253, 23
	v_add3_u32 v105, v3, v6, v7
	v_bitop3_b32 v7, v106, 28, v5 bitop3:0x48
	v_or_b32_e32 v108, 56, v94
	v_readlane_b32 s37, v253, 19
	v_readlane_b32 s38, v253, 20
	v_readlane_b32 s39, v253, 21
	v_readlane_b32 s42, v253, 24
	v_readlane_b32 s43, v253, 25
	v_readlane_b32 s44, v253, 26
	v_readlane_b32 s45, v253, 27
	v_readlane_b32 s46, v253, 28
	v_readlane_b32 s47, v253, 29
	v_readlane_b32 s48, v253, 30
	v_readlane_b32 s49, v253, 31
	v_readlane_b32 s50, v253, 32
	v_readlane_b32 s51, v253, 33
	s_cmp_lg_u64 s[40:41], 0
	v_and_b32_e32 v2, 60, v5
	v_lshlrev_b32_e32 v6, 7, v106
	v_lshlrev_b32_e32 v7, 2, v7
	v_bitop3_b32 v5, v108, 28, v5 bitop3:0x48
	s_cselect_b64 s[6:7], -1, 0
	s_cmp_lg_u64 s[44:45], 0
	v_readlane_b32 s36, v253, 2
	v_add3_u32 v107, v3, v6, v7
	v_lshlrev_b32_e32 v6, 7, v108
	v_lshlrev_b32_e32 v5, 2, v5
	v_readlane_b32 s40, v253, 6
	v_readlane_b32 s41, v253, 7
	v_lshlrev_b32_e32 v67, 1, v4
	v_add3_u32 v109, v3, v6, v5
	v_lshlrev_b32_e32 v3, 11, v4
	v_lshlrev_b32_e32 v4, 12, v4
	s_cselect_b64 s[8:9], -1, 0
	v_readlane_b32 s37, v253, 3
	v_readlane_b32 s38, v253, 4
	v_readlane_b32 s39, v253, 5
	s_cmp_lg_u64 s[40:41], 0
	v_lshlrev_b32_e32 v5, 2, v11
	v_readlane_b32 s0, v253, 34
	s_movk_i32 s16, 0xf000
	v_mov_b32_e32 v69, 0
	v_lshlrev_b32_e32 v86, 7, v2
	v_and_b32_e32 v70, 56, v12
	s_cselect_b64 s[12:13], -1, 0
	v_lshl_add_u32 v110, v11, 6, s24
	s_lshl_b32 s11, s10, 6
	v_lshl_add_u32 v111, s0, 5, v5
	s_lshl_b32 s36, s10, 2
	v_mov_b64_e32 v[72:73], s[92:93]
	s_movk_i32 s37, 0x2000
	s_mov_b32 s38, 0x10000
	s_mov_b32 s39, 0x12000
	s_mov_b32 s2, 0x20000
	s_mov_b32 s3, 0x22000
	s_mov_b32 s76, 0x30000
	s_mov_b32 s77, 0x32000
	s_mov_b32 s78, 0x40000
	s_mov_b32 s79, 0x42000
	s_mov_b32 s80, 0x50000
	s_mov_b32 s81, 0x52000
	s_mov_b32 s82, 0x60000
	s_mov_b32 s83, 0x62000
	s_mov_b32 s84, 0x70000
	v_lshlrev_b32_e32 v112, 2, v3
	s_mov_b32 s85, 0x39000
	v_lshlrev_b32_e32 v113, 2, v4
	s_mov_b32 s86, 0x48000
	s_mov_b32 s87, 0x80000
	s_mov_b32 s88, 0x88000
	s_mov_b32 s89, 0xc0000
	s_mov_b32 s56, 0xc8000
	s_mov_b32 s57, 0x100000
	s_mov_b32 s58, 0x108000
	s_mov_b32 s59, 0x140000
	s_mov_b32 s60, 0x148000
	s_mov_b32 s61, 0x180000
	s_mov_b32 s64, 0x1400000
	s_mov_b32 s65, 0x14000
	s_mov_b32 s66, 0x16000
	s_mov_b32 s67, 0x2a000
	s_mov_b32 s68, 0x3c000
	s_mov_b32 s69, 0x3e000
	v_lshlrev_b32_e32 v68, 2, v2
	v_mov_b32_e32 v114, 6
	s_mov_b32 s70, 0x64000
	s_mov_b32 s71, 0x66000
	s_mov_b32 s72, 0x78000
	s_mov_b32 s73, 0x29ff
	s_mov_b64 s[14:15], 0
	s_mov_b32 s17, -1
	s_mov_b64 s[18:19], 0xc00000
	s_mov_b64 s[20:21], 0xa00000
	s_mov_b64 s[22:23], 0x3400000
	s_mov_b64 s[24:25], 0x1400000
	v_readlane_b32 s42, v253, 8
	v_readlane_b32 s43, v253, 9
	v_readlane_b32 s44, v253, 10
	v_readlane_b32 s45, v253, 11
	v_readlane_b32 s46, v253, 12
	v_readlane_b32 s47, v253, 13
	v_readlane_b32 s48, v253, 14
	v_readlane_b32 s49, v253, 15
	v_readlane_b32 s50, v253, 16
	v_readlane_b32 s51, v253, 17
	s_branch .LBB0_118

; __device__ __forceinline__ void p0_transpose_item(const float* W, int K, int N, const float* gain, const float* gain2  , bf16_t* WT, LAS unsigned* scr, int item, int lane) {
;     const int nblk = N / 64, kb = item / nblk, nb = item % nblk, k0 = 64 * kb, n0 = 64 * nb;
;     if (gain2 && k0 >= 1024) gain = gain2 - 1024;
;     const int n4 = lane & 15, kq = lane >> 4;
;     f32x4 r0[8], r1[8];
;     const float* src = W + (size_t)(k0 + 2 * kq) * N + n0 + 4 * n4;
; __device__ __forceinline__ void p0_prologue(const Params& p, LAS unsigned char* lds, int tid) {
;     ...
;     for (int it = gw; it < I_LAYER * DEPTH; it += NGW) {
;         const int l = it / I_LAYER; int r = it % I_LAYER;
;         unsigned char* wl = p.ws + (size_t)l * LAYER_BYTES;
;         if (r < I_IN) { p0_transpose_item(p.in[3] + (size_t)l * DM * INW, DM, INW, p.in[2] + l * DM, nullptr, (bf16_t*)(wl + LO_WIN), scr, r, lane); continue; } r -= I_IN;
;         if (r < I_UP) { p0_transpose_item(p.in[21] + (size_t)l * DM * DFF, DM, DFF, p.in[20] + l * DM, nullptr, (bf16_t*)(wl + LO_WUP), scr, r, lane); continue; } r -= I_UP;
;         if (r < I_DN) { p0_transpose_item(p.in[22] + (size_t)l * DFF * DM, DFF, DM, nullptr, nullptr, (bf16_t*)(wl + LO_WDN), scr, r, lane); continue; } r -= I_DN;
;         if (r < I_GLU) { p0_transpose_item(p.in[15] + (size_t)l * 1024 * 1024, 1024, 1024, nullptr, nullptr, (bf16_t*)(wl + LO_WGLU), scr, r, lane); continue; } r -= I_GLU;
;         p0_transpose_item(p.in[19] + (size_t)l * DM * DM, DM, DM, p.in[17] + l * 1024, p.in[18] + l * 1024, (bf16_t*)(wl + LO_WOUT), scr, r, lane);
;     }
.Lmy_w_entry:
	s_mov_b32 s0, s98
	v_cmp_gt_i32_e32 vcc, s0, v90
	s_and_saveexec_b64 s[4:5], vcc
	s_cbranch_execz .Lmy_w181
	v_lshl_add_u32 v27, v35, 13, 0
	v_lshrrev_b32_e32 v28, 4, v34
	v_lshlrev_b32_e32 v31, 4, v201
	v_lshl_add_u32 v30, v28, 2, v27
	v_and_b32_e32 v31, 0x70, v31
	s_movk_i32 s1, 0x50
	v_lshlrev_b32_e32 v29, 2, v34
	s_movk_i32 s0, 0x70
	v_xad_u32 v115, v31, s1, v30
	s_movk_i32 s1, 0x60
	v_lshrrev_b32_e32 v118, 3, v34
	v_add_u32_e32 v95, v30, v31
	v_xad_u32 v111, v31, 16, v30
	v_xad_u32 v112, v31, 32, v30
	v_xad_u32 v113, v31, 48, v30
	v_xad_u32 v114, v31, 64, v30
	v_xad_u32 v116, v31, s1, v30
	v_xad_u32 v117, v31, s0, v30
	v_bitop3_b32 v31, v118, 28, v29 bitop3:0x48
	v_or_b32_e32 v120, 8, v118
	v_lshlrev_b32_e32 v30, 7, v118
	v_lshlrev_b32_e32 v31, 2, v31
	v_bitop3_b32 v32, v120, 28, v29 bitop3:0x48
	v_add3_u32 v119, v27, v30, v31
	v_lshlrev_b32_e32 v30, 7, v120
	v_lshlrev_b32_e32 v32, 2, v32
	v_or_b32_e32 v122, 16, v118
	v_add3_u32 v121, v27, v30, v32
	v_bitop3_b32 v32, v122, 28, v29 bitop3:0x48
	v_lshlrev_b32_e32 v30, 7, v122
	v_lshlrev_b32_e32 v32, 2, v32
	v_or_b32_e32 v124, 24, v118
	v_add3_u32 v123, v27, v30, v32
	v_bitop3_b32 v32, v124, 28, v29 bitop3:0x48
	v_lshlrev_b32_e32 v30, 7, v124
	v_lshlrev_b32_e32 v32, 2, v32
	v_or_b32_e32 v126, 32, v118
	v_add3_u32 v125, v27, v30, v32
	v_lshlrev_b32_e32 v30, 7, v126
	v_or_b32_e32 v128, 40, v118
	v_add3_u32 v127, v27, v30, v31
	v_bitop3_b32 v31, v128, 28, v29 bitop3:0x48
	v_readlane_b32 s36, v253, 18
	v_lshlrev_b32_e32 v30, 7, v128
	v_lshlrev_b32_e32 v31, 2, v31
	v_or_b32_e32 v130, 48, v118
	v_readlane_b32 s40, v253, 22
	v_readlane_b32 s41, v253, 23
	v_add3_u32 v129, v27, v30, v31
	v_bitop3_b32 v31, v130, 28, v29 bitop3:0x48
	v_or_b32_e32 v132, 56, v118
	v_readlane_b32 s37, v253, 19
	v_readlane_b32 s38, v253, 20
	v_readlane_b32 s39, v253, 21
	v_readlane_b32 s42, v253, 24
	v_readlane_b32 s43, v253, 25
	v_readlane_b32 s44, v253, 26
	v_readlane_b32 s45, v253, 27
	v_readlane_b32 s46, v253, 28
	v_readlane_b32 s47, v253, 29
	v_readlane_b32 s48, v253, 30
	v_readlane_b32 s49, v253, 31
	v_readlane_b32 s50, v253, 32
	v_readlane_b32 s51, v253, 33
	s_cmp_lg_u64 s[40:41], 0
	v_and_b32_e32 v26, 60, v29
	v_lshlrev_b32_e32 v30, 7, v130
	v_lshlrev_b32_e32 v31, 2, v31
	v_bitop3_b32 v29, v132, 28, v29 bitop3:0x48
	s_cselect_b64 s[6:7], -1, 0
	s_cmp_lg_u64 s[44:45], 0
	v_readlane_b32 s36, v253, 2
	v_add3_u32 v131, v27, v30, v31
	v_lshlrev_b32_e32 v30, 7, v132
	v_lshlrev_b32_e32 v29, 2, v29
	v_readlane_b32 s40, v253, 6
	v_readlane_b32 s41, v253, 7
	v_lshlrev_b32_e32 v91, 1, v28
	v_add3_u32 v133, v27, v30, v29
	v_lshlrev_b32_e32 v27, 11, v28
	v_lshlrev_b32_e32 v28, 12, v28
	s_cselect_b64 s[8:9], -1, 0
	v_readlane_b32 s37, v253, 3
	v_readlane_b32 s38, v253, 4
	v_readlane_b32 s39, v253, 5
	s_cmp_lg_u64 s[40:41], 0
	v_lshlrev_b32_e32 v29, 2, v35
	v_readlane_b32 s0, v253, 34
	s_movk_i32 s16, 0xf000
	v_mov_b32_e32 v93, 0
	v_lshlrev_b32_e32 v110, 7, v26
	v_and_b32_e32 v94, 56, v36
	s_cselect_b64 s[12:13], -1, 0
	v_lshlrev_b32_e32 v134, 6, v90
	s_lshl_b32 s11, s10, 6
	v_lshlrev_b32_e32 v135, 2, v90
	s_lshl_b32 s36, s10, 2
	v_mov_b64_e32 v[96:97], s[92:93]
	s_movk_i32 s37, 0x2000
	s_mov_b32 s38, 0x10000
	s_mov_b32 s39, 0x12000
	s_mov_b32 s2, 0x20000
	s_mov_b32 s3, 0x22000
	s_mov_b32 s76, 0x30000
	s_mov_b32 s77, 0x32000
	s_mov_b32 s78, 0x40000
	s_mov_b32 s79, 0x42000
	s_mov_b32 s80, 0x50000
	s_mov_b32 s81, 0x52000
	s_mov_b32 s82, 0x60000
	s_mov_b32 s83, 0x62000
	s_mov_b32 s84, 0x70000
	v_lshlrev_b32_e32 v136, 2, v27
	s_mov_b32 s85, 0x39000
	v_lshlrev_b32_e32 v137, 2, v28
	s_mov_b32 s86, 0x48000
	s_mov_b32 s87, 0x80000
	s_mov_b32 s88, 0x88000
	s_mov_b32 s89, 0xc0000
	s_mov_b32 s56, 0xc8000
	s_mov_b32 s57, 0x100000
	s_mov_b32 s58, 0x108000
	s_mov_b32 s59, 0x140000
	s_mov_b32 s60, 0x148000
	s_mov_b32 s61, 0x180000
	s_mov_b32 s64, 0x1400000
	s_mov_b32 s65, 0x14000
	s_mov_b32 s66, 0x16000
	s_mov_b32 s67, 0x2a000
	s_mov_b32 s68, 0x3c000
	s_mov_b32 s69, 0x3e000
	v_lshlrev_b32_e32 v92, 2, v26
	v_mov_b32_e32 v138, 6
	s_mov_b32 s70, 0x64000
	s_mov_b32 s71, 0x66000
	s_mov_b32 s72, 0x78000
	s_mov_b32 s73, s99
	s_mov_b64 s[14:15], 0
	s_mov_b32 s17, -1
	s_mov_b64 s[18:19], 0xc00000
	s_mov_b64 s[20:21], 0xa00000
	s_mov_b64 s[22:23], 0x3400000
	s_mov_b64 s[24:25], 0x1400000
	v_readlane_b32 s42, v253, 8
	v_readlane_b32 s43, v253, 9
	v_readlane_b32 s44, v253, 10
	v_readlane_b32 s45, v253, 11
	v_readlane_b32 s46, v253, 12
	v_readlane_b32 s47, v253, 13
	v_readlane_b32 s48, v253, 14
	v_readlane_b32 s49, v253, 15
	v_readlane_b32 s50, v253, 16
	v_readlane_b32 s51, v253, 17
	s_branch .Lmy_w118
; #define LAS __attribute__((address_space(3)))
; __device__ __forceinline__ void p0_transpose_item(const float* W, int K, int N, const float* gain, const float* gain2  , bf16_t* WT, LAS unsigned* scr, int item, int lane) {
;     ...
;     asm volatile("s_waitcnt lgkmcnt(0)" ::: "memory");
; #pragma unroll
;     for (int it = 0; it < 8; ++it) {
;         const int n = (lane >> 3) + 8 * it, c = lane & 7;
;         const u32x4 v = *(const LAS u32x4*)(scr + n * 32 + ((c ^ ((n >> 2) & 7)) << 2));
;         *(u32x4*)(WT + (size_t)(n0 + n) * K + k0 + 8 * c) = v;
;     }
;     asm volatile("s_waitcnt lgkmcnt(0)" ::: "memory");
; }
; __device__ __forceinline__ void p0_prologue(const Params& p, LAS unsigned char* lds, int tid) {
;     ...
;     for (int it = gw; it < I_LAYER * DEPTH; it += NGW) {
;         const int l = it / I_LAYER; int r = it % I_LAYER;
;         unsigned char* wl = p.ws + (size_t)l * LAYER_BYTES;
;         if (r < I_IN) { p0_transpose_item(p.in[3] + (size_t)l * DM * INW, DM, INW, p.in[2] + l * DM, nullptr, (bf16_t*)(wl + LO_WIN), scr, r, lane); continue; } r -= I_IN;
;         if (r < I_UP) { p0_transpose_item(p.in[21] + (size_t)l * DM * DFF, DM, DFF, p.in[20] + l * DM, nullptr, (bf16_t*)(wl + LO_WUP), scr, r, lane); continue; } r -= I_UP;
;         if (r < I_DN) { p0_transpose_item(p.in[22] + (size_t)l * DFF * DM, DFF, DM, nullptr, nullptr, (bf16_t*)(wl + LO_WDN), scr, r, lane); continue; } r -= I_DN;
;         if (r < I_GLU) { p0_transpose_item(p.in[15] + (size_t)l * 1024 * 1024, 1024, 1024, nullptr, nullptr, (bf16_t*)(wl + LO_WGLU), scr, r, lane); continue; } r -= I_GLU;
;         p0_transpose_item(p.in[19] + (size_t)l * DM * DM, DM, DM, p.in[17] + l * 1024, p.in[18] + l * 1024, (bf16_t*)(wl + LO_WOUT), scr, r, lane);
.Lmy_w116:
	s_waitcnt vmcnt(0)
	v_mul_f32_e32 v26, v26, v42
	v_mul_f32_e32 v30, v30, v43
	v_cvt_pk_bf16_f32 v26, v26, v30
	v_add_u32_e32 v30, v117, v110
	ds_write_b32 v30, v26
	v_mul_f32_e32 v26, v27, v42
	v_mul_f32_e32 v27, v31, v43
	v_cvt_pk_bf16_f32 v26, v26, v27
	ds_write_b32 v30, v26 offset:128
	v_mul_f32_e32 v26, v28, v42
	v_mul_f32_e32 v27, v32, v43
	v_cvt_pk_bf16_f32 v26, v26, v27
	ds_write_b32 v30, v26 offset:256
	v_mul_f32_e32 v26, v29, v42
	v_mul_f32_e32 v27, v33, v43
	v_cvt_pk_bf16_f32 v26, v26, v27
	ds_write_b32 v30, v26 offset:384
	v_ashrrev_i32_e32 v105, 31, v104
	s_waitcnt lgkmcnt(0)
	v_lshl_add_u64 v[26:27], v[104:105], 1, v[98:99]
	v_lshlrev_b32_e32 v28, 1, v94
	v_mov_b32_e32 v29, v93
	v_lshl_add_u64 v[34:35], v[26:27], 0, v[28:29]
	ds_read_b128 v[26:29], v119
	v_or_b32_e32 v30, v102, v118
	v_ashrrev_i32_e32 v31, 31, v30
	v_lshlrev_b64 v[30:31], 12, v[30:31]
	v_lshl_add_u64 v[36:37], v[34:35], 0, v[30:31]
	ds_read_b128 v[30:33], v121
	s_waitcnt lgkmcnt(1)
	global_store_dwordx4 v[36:37], v[26:29], off
	s_nop 1
	v_or_b32_e32 v26, v102, v120
	v_ashrrev_i32_e32 v27, 31, v26
	v_lshlrev_b64 v[26:27], 12, v[26:27]
	v_lshl_add_u64 v[26:27], v[34:35], 0, v[26:27]
	s_waitcnt lgkmcnt(0)
	global_store_dwordx4 v[26:27], v[30:33], off
	ds_read_b128 v[26:29], v123
	s_nop 0
	v_or_b32_e32 v30, v102, v122
	v_ashrrev_i32_e32 v31, 31, v30
	v_lshlrev_b64 v[30:31], 12, v[30:31]
	v_lshl_add_u64 v[36:37], v[34:35], 0, v[30:31]
	ds_read_b128 v[30:33], v125
	s_waitcnt lgkmcnt(1)
	global_store_dwordx4 v[36:37], v[26:29], off
	s_nop 1
	v_or_b32_e32 v26, v102, v124
	v_ashrrev_i32_e32 v27, 31, v26
	v_lshlrev_b64 v[26:27], 12, v[26:27]
	v_lshl_add_u64 v[26:27], v[34:35], 0, v[26:27]
	s_waitcnt lgkmcnt(0)
	global_store_dwordx4 v[26:27], v[30:33], off
	ds_read_b128 v[26:29], v127
	s_nop 0
	v_or_b32_e32 v30, v102, v126
	v_ashrrev_i32_e32 v31, 31, v30
	v_lshlrev_b64 v[30:31], 12, v[30:31]
	v_lshl_add_u64 v[36:37], v[34:35], 0, v[30:31]
	ds_read_b128 v[30:33], v129
	s_waitcnt lgkmcnt(1)
	global_store_dwordx4 v[36:37], v[26:29], off
	s_nop 1
	v_or_b32_e32 v26, v102, v128
	v_ashrrev_i32_e32 v27, 31, v26
	v_lshlrev_b64 v[26:27], 12, v[26:27]
	v_lshl_add_u64 v[26:27], v[34:35], 0, v[26:27]
	s_waitcnt lgkmcnt(0)
	global_store_dwordx4 v[26:27], v[30:33], off
	ds_read_b128 v[26:29], v131
	s_nop 0
	v_or_b32_e32 v30, v102, v130
	v_ashrrev_i32_e32 v31, 31, v30
	v_lshlrev_b64 v[30:31], 12, v[30:31]
	v_lshl_add_u64 v[36:37], v[34:35], 0, v[30:31]
	ds_read_b128 v[30:33], v133
	s_waitcnt lgkmcnt(1)
	global_store_dwordx4 v[36:37], v[26:29], off
	s_nop 1
	v_or_b32_e32 v26, v102, v132
	v_ashrrev_i32_e32 v27, 31, v26
	v_lshlrev_b64 v[26:27], 12, v[26:27]
	v_lshl_add_u64 v[26:27], v[34:35], 0, v[26:27]
	s_waitcnt lgkmcnt(0)
	global_store_dwordx4 v[26:27], v[30:33], off
	s_waitcnt lgkmcnt(0)
.Lmy_w117:
	s_or_b64 exec, exec, s[26:27]
	v_add_u32_e32 v90, s10, v90
	v_cmp_lt_i32_e32 vcc, s73, v90
	v_add_u32_e32 v134, s11, v134
	s_or_b64 s[14:15], vcc, s[14:15]
	v_add_u32_e32 v135, s36, v135
	s_andn2_b64 exec, exec, s[14:15]
	s_cbranch_execz .Lmy_w181
.Lmy_w118:
	s_mov_b32 s0, 0x30c30c31
	v_mul_hi_i32 v26, v90, s0
	v_lshrrev_b32_e32 v27, 31, v26
	v_ashrrev_i32_e32 v26, 11, v26
	v_add_u32_e32 v100, v26, v27
	s_mov_b32 s0, 0x6400000
	v_mul_i32_i24_e32 v27, 0x2a00, v100
	v_mad_i64_i32 v[98:99], s[0:1], v100, s0, v[96:97]
	v_sub_u32_e32 v26, v90, v27
	s_movk_i32 s0, 0x4ff
	v_ashrrev_i32_e32 v101, 31, v100
	v_cmp_lt_i32_e32 vcc, s0, v26
	s_and_saveexec_b64 s[0:1], vcc
	s_xor_b64 s[26:27], exec, s[0:1]
	s_cbranch_execz .Lmy_w164
	s_movk_i32 s0, 0x14ff
	v_cmp_lt_u32_e32 vcc, s0, v26
	s_and_saveexec_b64 s[0:1], vcc
	s_xor_b64 s[0:1], exec, s[0:1]
	s_cbranch_execz .Lmy_w145
	s_movk_i32 s28, 0x24ff
	v_cmp_lt_u32_e32 vcc, s28, v26
	s_and_saveexec_b64 s[28:29], vcc
	s_xor_b64 s[28:29], exec, s[28:29]
	s_cbranch_execz .Lmy_w142
	s_movk_i32 s30, 0x25ff
	v_cmp_lt_u32_e32 vcc, s30, v26
	s_and_saveexec_b64 s[30:31], vcc
	s_xor_b64 s[30:31], exec, s[30:31]
	s_cbranch_execz .Lmy_w139
	v_add_u16_e32 v104, 0xda00, v26
	v_lshrrev_b16_e32 v26, 5, v104
	v_readlane_b32 s40, v253, 18
	v_lshlrev_b32_e32 v109, 6, v26
	v_lshlrev_b32_e32 v26, 6, v27
	v_lshlrev_b64 v[28:29], 24, v[100:101]
	v_readlane_b32 s46, v253, 24
	v_readlane_b32 s47, v253, 25
	v_sub_u32_e32 v26, v134, v26
	v_or_b32_e32 v105, v109, v91
	v_lshl_add_u64 v[28:29], s[46:47], 0, v[28:29]
	v_and_b32_e32 v108, 0x7c0, v26
	v_lshlrev_b32_e32 v26, 13, v105
	v_mov_b32_e32 v27, v93
	v_lshl_add_u64 v[26:27], v[28:29], 0, v[26:27]
	v_lshlrev_b32_e32 v28, 2, v108
	v_mov_b32_e32 v29, v93
	v_lshl_add_u64 v[26:27], v[26:27], 0, v[28:29]
	v_lshl_add_u64 v[26:27], v[26:27], 0, v[92:93]
	v_add_co_u32_e32 v28, vcc, s37, v26
	v_lshlrev_b32_e32 v100, 10, v100
	s_nop 0
	v_addc_co_u32_e32 v29, vcc, 0, v27, vcc
	global_load_dwordx4 v[82:85], v[26:27], off nt
	global_load_dwordx4 v[86:89], v[28:29], off nt
	v_add_co_u32_e32 v28, vcc, s38, v26
	v_ashrrev_i32_e32 v101, 31, v100
	s_nop 0
	v_addc_co_u32_e32 v29, vcc, 0, v27, vcc
	v_add_co_u32_e32 v30, vcc, s39, v26
	v_readlane_b32 s42, v253, 20
	s_nop 0
	v_addc_co_u32_e32 v31, vcc, 0, v27, vcc
	global_load_dwordx4 v[74:77], v[28:29], off nt
	global_load_dwordx4 v[78:81], v[30:31], off nt
	v_add_co_u32_e32 v28, vcc, s2, v26
	v_readlane_b32 s43, v253, 21
	s_nop 0
	v_addc_co_u32_e32 v29, vcc, 0, v27, vcc
	v_add_co_u32_e32 v30, vcc, s3, v26
	v_readlane_b32 s44, v253, 22
	s_nop 0
	v_addc_co_u32_e32 v31, vcc, 0, v27, vcc
	global_load_dwordx4 v[66:69], v[28:29], off nt
	global_load_dwordx4 v[70:73], v[30:31], off nt
	v_add_co_u32_e32 v28, vcc, s76, v26
	v_readlane_b32 s45, v253, 23
	s_nop 0
	v_addc_co_u32_e32 v29, vcc, 0, v27, vcc
	v_add_co_u32_e32 v30, vcc, s77, v26
	v_lshlrev_b64 v[100:101], 2, v[100:101]
	s_nop 0
	v_addc_co_u32_e32 v31, vcc, 0, v27, vcc
	global_load_dwordx4 v[58:61], v[28:29], off nt
	global_load_dwordx4 v[62:65], v[30:31], off nt
	v_add_co_u32_e32 v28, vcc, s78, v26
	s_movk_i32 s34, 0x1ff
	s_nop 0
	v_addc_co_u32_e32 v29, vcc, 0, v27, vcc
	v_add_co_u32_e32 v30, vcc, s79, v26
	v_lshl_add_u64 v[102:103], s[42:43], 0, v[100:101]
	s_nop 0
	v_addc_co_u32_e32 v31, vcc, 0, v27, vcc
	global_load_dwordx4 v[50:53], v[28:29], off nt
	s_waitcnt lgkmcnt(0)
; __device__ __forceinline__ unsigned pk2(float lo, float hi) { unsigned r; asm volatile("v_cvt_pk_bf16_f32 %0, %1, %2" : "=v"(r) : "v"(lo), "v"(hi)); return r; }
; __device__ __forceinline__ void p0_transpose_item(const float* W, int K, int N, const float* gain, const float* gain2  , bf16_t* WT, LAS unsigned* scr, int item, int lane) {
;     const int nblk = N / 64, kb = item / nblk, nb = item % nblk, k0 = 64 * kb, n0 = 64 * nb;
;     if (gain2 && k0 >= 1024) gain = gain2 - 1024;
;     const int n4 = lane & 15, kq = lane >> 4;
;     f32x4 r0[8], r1[8];
;     const float* src = W + (size_t)(k0 + 2 * kq) * N + n0 + 4 * n4;
; #pragma unroll
;     for (int j = 0; j < 8; ++j) { r0[j] = __builtin_nontemporal_load((const f32x4*)(src + (size_t)(8 * j) * N)); r1[j] = __builtin_nontemporal_load((const f32x4*)(src + (size_t)(8 * j + 1) * N)); }
; #pragma unroll
;     for (int j = 0; j < 8; ++j) {
;         float g0 = 1.f, g1 = 1.f; if (gain) { g0 = gain[k0 + 8 * j + 2 * kq]; g1 = gain[k0 + 8 * j + 2 * kq + 1]; }
; #pragma unroll
;         for (int i = 0; i < 4; ++i) scr[(4 * n4 + i) * 32 + (((j ^ (n4 & 7)) << 2) | kq)] = pk2(r0[j][i] * g0, r1[j][i] * g1);
;     }
	global_load_dwordx4 v[54:57], v[30:31], off nt
	v_add_co_u32_e32 v28, vcc, s80, v26
	v_lshl_add_u64 v[100:101], s[44:45], 0, v[100:101]
	s_nop 0
	v_addc_co_u32_e32 v29, vcc, 0, v27, vcc
	v_add_co_u32_e32 v30, vcc, s81, v26
	v_lshl_add_u64 v[100:101], v[100:101], 0, s[16:17]
	s_nop 0
	v_addc_co_u32_e32 v31, vcc, 0, v27, vcc
	global_load_dwordx4 v[42:45], v[28:29], off nt
	global_load_dwordx4 v[46:49], v[30:31], off nt
	v_add_co_u32_e32 v28, vcc, s82, v26
	v_mov_b32_e32 v106, 1.0
	s_nop 0
	v_addc_co_u32_e32 v29, vcc, 0, v27, vcc
	v_add_co_u32_e32 v30, vcc, s83, v26
	v_mov_b32_e32 v107, 1.0
	s_nop 0
	v_addc_co_u32_e32 v31, vcc, 0, v27, vcc
	global_load_dwordx4 v[34:37], v[28:29], off nt
	global_load_dwordx4 v[38:41], v[30:31], off nt
	v_add_co_u32_e32 v28, vcc, s84, v26
	v_readlane_b32 s41, v253, 19
	s_nop 0
	v_addc_co_u32_e32 v29, vcc, 0, v27, vcc
	v_add_co_u32_e32 v30, vcc, 0x72000, v26
	v_readlane_b32 s48, v253, 26
	s_nop 0
	v_addc_co_u32_e32 v31, vcc, 0, v27, vcc
	global_load_dwordx4 v[26:29], v[28:29], off nt
	s_nop 0
	global_load_dwordx4 v[30:33], v[30:31], off nt
	v_cmp_lt_u16_e32 vcc, s34, v104
	s_and_b64 vcc, s[6:7], vcc
	v_mov_b32_e32 v104, 1.0
	v_cndmask_b32_e32 v101, v103, v101, vcc
	v_cndmask_b32_e32 v100, v102, v100, vcc
	v_cmp_ne_u64_e32 vcc, 0, v[100:101]
	v_lshlrev_b32_e32 v102, 2, v105
	v_readlane_b32 s49, v253, 27
	v_readlane_b32 s50, v253, 28
	v_readlane_b32 s51, v253, 29
	v_readlane_b32 s52, v253, 30
	v_readlane_b32 s53, v253, 31
	v_readlane_b32 s54, v253, 32
	v_readlane_b32 s55, v253, 33
	s_and_saveexec_b64 s[34:35], vcc
	s_cbranch_execz .Lmy_w124
	v_mov_b32_e32 v103, v93
	v_lshl_add_u64 v[106:107], v[100:101], 0, v[102:103]
	global_load_dwordx2 v[106:107], v[106:107], off
.Lmy_w124:
	s_or_b64 exec, exec, s[34:35]
	s_waitcnt vmcnt(0)
	v_mul_f32_e32 v82, v82, v106
	v_mul_f32_e32 v86, v86, v107
	v_cvt_pk_bf16_f32 v82, v82, v86
	v_add_u32_e32 v86, v95, v110
	ds_write_b32 v86, v82
	v_mul_f32_e32 v82, v83, v106
	v_mul_f32_e32 v83, v87, v107
	v_cvt_pk_bf16_f32 v82, v82, v83
	ds_write_b32 v86, v82 offset:128
	v_mul_f32_e32 v82, v84, v106
	v_mul_f32_e32 v83, v88, v107
	v_cvt_pk_bf16_f32 v82, v82, v83
	ds_write_b32 v86, v82 offset:256
	v_mul_f32_e32 v82, v85, v106
	v_mov_b32_e32 v105, 1.0
	v_mul_f32_e32 v83, v89, v107
	v_cvt_pk_bf16_f32 v82, v82, v83
	ds_write_b32 v86, v82 offset:384
	s_and_saveexec_b64 s[34:35], vcc
	s_cbranch_execz .Lmy_w126
	v_mov_b32_e32 v103, v93
	v_lshl_add_u64 v[82:83], v[100:101], 0, v[102:103]
	global_load_dwordx2 v[104:105], v[82:83], off offset:32
.Lmy_w126:
	s_or_b64 exec, exec, s[34:35]
	s_waitcnt vmcnt(0)
	v_mul_f32_e32 v74, v74, v104
	v_mul_f32_e32 v78, v78, v105
	v_cvt_pk_bf16_f32 v74, v74, v78
	v_add_u32_e32 v78, v111, v110
	ds_write_b32 v78, v74
	v_mul_f32_e32 v74, v75, v104
	v_mul_f32_e32 v75, v79, v105
	v_cvt_pk_bf16_f32 v74, v74, v75
	ds_write_b32 v78, v74 offset:128
	v_mul_f32_e32 v74, v76, v104
	v_mul_f32_e32 v75, v80, v105
	v_cvt_pk_bf16_f32 v74, v74, v75
	ds_write_b32 v78, v74 offset:256
	v_mul_f32_e32 v74, v77, v104
	v_mul_f32_e32 v75, v81, v105
	v_cvt_pk_bf16_f32 v74, v74, v75
	ds_write_b32 v78, v74 offset:384
	v_mov_b32_e32 v74, 1.0
	v_mov_b32_e32 v76, 1.0
	v_mov_b32_e32 v77, 1.0
	s_and_saveexec_b64 s[34:35], vcc
	s_cbranch_execz .Lmy_w128
	v_mov_b32_e32 v103, v93
	v_lshl_add_u64 v[76:77], v[100:101], 0, v[102:103]
	global_load_dwordx2 v[76:77], v[76:77], off offset:64
.Lmy_w128:
	s_or_b64 exec, exec, s[34:35]
	s_waitcnt vmcnt(0)
	v_mul_f32_e32 v66, v66, v76
	v_mul_f32_e32 v70, v70, v77
	v_cvt_pk_bf16_f32 v66, v66, v70
	v_add_u32_e32 v70, v112, v110
	ds_write_b32 v70, v66
	v_mul_f32_e32 v66, v67, v76
	v_mul_f32_e32 v67, v71, v77
	v_cvt_pk_bf16_f32 v66, v66, v67
	ds_write_b32 v70, v66 offset:128
	v_mul_f32_e32 v66, v68, v76
	v_mul_f32_e32 v67, v72, v77
	v_cvt_pk_bf16_f32 v66, v66, v67
	ds_write_b32 v70, v66 offset:256
	v_mul_f32_e32 v66, v69, v76
	v_mov_b32_e32 v75, 1.0
	v_mul_f32_e32 v67, v73, v77
	v_cvt_pk_bf16_f32 v66, v66, v67
	ds_write_b32 v70, v66 offset:384
	s_and_saveexec_b64 s[34:35], vcc
	s_cbranch_execz .Lmy_w130
	v_mov_b32_e32 v103, v93
	v_lshl_add_u64 v[66:67], v[100:101], 0, v[102:103]
	global_load_dwordx2 v[74:75], v[66:67], off offset:96
.Lmy_w130:
	s_or_b64 exec, exec, s[34:35]
	s_waitcnt vmcnt(0)
	v_mul_f32_e32 v58, v58, v74
	v_mul_f32_e32 v62, v62, v75
	v_cvt_pk_bf16_f32 v58, v58, v62
	v_add_u32_e32 v62, v113, v110
	ds_write_b32 v62, v58
	v_mul_f32_e32 v58, v59, v74
	v_mul_f32_e32 v59, v63, v75
	v_cvt_pk_bf16_f32 v58, v58, v59
	ds_write_b32 v62, v58 offset:128
	v_mul_f32_e32 v58, v60, v74
	v_mul_f32_e32 v59, v64, v75
	v_cvt_pk_bf16_f32 v58, v58, v59
	ds_write_b32 v62, v58 offset:256
	v_mul_f32_e32 v58, v61, v74
	v_mul_f32_e32 v59, v65, v75
	v_cvt_pk_bf16_f32 v58, v58, v59
	ds_write_b32 v62, v58 offset:384
	v_mov_b32_e32 v58, 1.0
	v_mov_b32_e32 v60, 1.0
	v_mov_b32_e32 v61, 1.0
	s_and_saveexec_b64 s[34:35], vcc
	s_cbranch_execz .Lmy_w132
	v_mov_b32_e32 v103, v93
	v_lshl_add_u64 v[60:61], v[100:101], 0, v[102:103]
	global_load_dwordx2 v[60:61], v[60:61], off offset:128
.Lmy_w132:
	s_or_b64 exec, exec, s[34:35]
	s_waitcnt vmcnt(0)
	v_mul_f32_e32 v50, v50, v60
	v_mul_f32_e32 v54, v54, v61
	v_cvt_pk_bf16_f32 v50, v50, v54
	v_add_u32_e32 v54, v114, v110
	ds_write_b32 v54, v50
	v_mul_f32_e32 v50, v51, v60
	v_mul_f32_e32 v51, v55, v61
	v_cvt_pk_bf16_f32 v50, v50, v51
	ds_write_b32 v54, v50 offset:128
	v_mul_f32_e32 v50, v52, v60
	v_mul_f32_e32 v51, v56, v61
	v_cvt_pk_bf16_f32 v50, v50, v51
	ds_write_b32 v54, v50 offset:256
	v_mul_f32_e32 v50, v53, v60
	v_mov_b32_e32 v59, 1.0
	v_mul_f32_e32 v51, v57, v61
	v_cvt_pk_bf16_f32 v50, v50, v51
	ds_write_b32 v54, v50 offset:384
	s_and_saveexec_b64 s[34:35], vcc
	s_cbranch_execz .Lmy_w134
	v_mov_b32_e32 v103, v93
	v_lshl_add_u64 v[50:51], v[100:101], 0, v[102:103]
	global_load_dwordx2 v[58:59], v[50:51], off offset:160
; #define LAS __attribute__((address_space(3)))
; __device__ __forceinline__ unsigned pk2(float lo, float hi) { unsigned r; asm volatile("v_cvt_pk_bf16_f32 %0, %1, %2" : "=v"(r) : "v"(lo), "v"(hi)); return r; }
; __device__ __forceinline__ void p0_transpose_item(const float* W, int K, int N, const float* gain, const float* gain2  , bf16_t* WT, LAS unsigned* scr, int item, int lane) {
;     ...
;     for (int j = 0; j < 8; ++j) {
;         float g0 = 1.f, g1 = 1.f; if (gain) { g0 = gain[k0 + 8 * j + 2 * kq]; g1 = gain[k0 + 8 * j + 2 * kq + 1]; }
; #pragma unroll
;         for (int i = 0; i < 4; ++i) scr[(4 * n4 + i) * 32 + (((j ^ (n4 & 7)) << 2) | kq)] = pk2(r0[j][i] * g0, r1[j][i] * g1);
;     }
;     asm volatile("s_waitcnt lgkmcnt(0)" ::: "memory");
; #pragma unroll
;     for (int it = 0; it < 8; ++it) {
;         const int n = (lane >> 3) + 8 * it, c = lane & 7;
;         const u32x4 v = *(const LAS u32x4*)(scr + n * 32 + ((c ^ ((n >> 2) & 7)) << 2));
;         *(u32x4*)(WT + (size_t)(n0 + n) * K + k0 + 8 * c) = v;
;     }
;     asm volatile("s_waitcnt lgkmcnt(0)" ::: "memory");
; }
.Lmy_w134:
	s_or_b64 exec, exec, s[34:35]
	s_waitcnt vmcnt(0)
	v_mul_f32_e32 v42, v42, v58
	v_mul_f32_e32 v46, v46, v59
	v_cvt_pk_bf16_f32 v42, v42, v46
	v_add_u32_e32 v46, v115, v110
	ds_write_b32 v46, v42
	v_mul_f32_e32 v42, v43, v58
	v_mul_f32_e32 v43, v47, v59
	v_cvt_pk_bf16_f32 v42, v42, v43
	ds_write_b32 v46, v42 offset:128
	v_mul_f32_e32 v42, v44, v58
	v_mul_f32_e32 v43, v48, v59
	v_cvt_pk_bf16_f32 v42, v42, v43
	ds_write_b32 v46, v42 offset:256
	v_mul_f32_e32 v42, v45, v58
	v_mul_f32_e32 v43, v49, v59
	v_cvt_pk_bf16_f32 v42, v42, v43
	ds_write_b32 v46, v42 offset:384
	v_mov_b32_e32 v42, 1.0
	v_mov_b32_e32 v44, 1.0
	v_mov_b32_e32 v45, 1.0
	s_and_saveexec_b64 s[34:35], vcc
	s_cbranch_execz .Lmy_w136
	v_mov_b32_e32 v103, v93
	v_lshl_add_u64 v[44:45], v[100:101], 0, v[102:103]
	global_load_dwordx2 v[44:45], v[44:45], off offset:192
.Lmy_w136:
	s_or_b64 exec, exec, s[34:35]
	s_waitcnt vmcnt(0)
	v_mul_f32_e32 v34, v34, v44
	v_mul_f32_e32 v38, v38, v45
	v_cvt_pk_bf16_f32 v34, v34, v38
	v_add_u32_e32 v38, v116, v110
	ds_write_b32 v38, v34
	v_mul_f32_e32 v34, v35, v44
	v_mul_f32_e32 v35, v39, v45
	v_cvt_pk_bf16_f32 v34, v34, v35
	ds_write_b32 v38, v34 offset:128
	v_mul_f32_e32 v34, v36, v44
	v_mul_f32_e32 v35, v40, v45
	v_cvt_pk_bf16_f32 v34, v34, v35
	ds_write_b32 v38, v34 offset:256
	v_mul_f32_e32 v34, v37, v44
	v_mov_b32_e32 v43, 1.0
	v_mul_f32_e32 v35, v41, v45
	v_cvt_pk_bf16_f32 v34, v34, v35
	ds_write_b32 v38, v34 offset:384
	s_and_saveexec_b64 s[34:35], vcc
	s_cbranch_execz .Lmy_w138
	v_mov_b32_e32 v103, v93
	v_lshl_add_u64 v[34:35], v[100:101], 0, v[102:103]
	global_load_dwordx2 v[42:43], v[34:35], off offset:224
.Lmy_w138:
	s_or_b64 exec, exec, s[34:35]
	s_waitcnt vmcnt(0)
	v_mul_f32_e32 v26, v26, v42
	v_mul_f32_e32 v30, v30, v43
	v_cvt_pk_bf16_f32 v26, v26, v30
	v_add_u32_e32 v30, v117, v110
	ds_write_b32 v30, v26
	v_mul_f32_e32 v26, v27, v42
	v_mul_f32_e32 v27, v31, v43
	v_cvt_pk_bf16_f32 v26, v26, v27
	ds_write_b32 v30, v26 offset:128
	v_mul_f32_e32 v26, v28, v42
	v_mul_f32_e32 v27, v32, v43
	v_cvt_pk_bf16_f32 v26, v26, v27
	ds_write_b32 v30, v26 offset:256
	v_mul_f32_e32 v26, v29, v42
	v_mul_f32_e32 v27, v33, v43
	v_cvt_pk_bf16_f32 v26, v26, v27
	ds_write_b32 v30, v26 offset:384
	v_lshlrev_b32_e32 v26, 1, v109
	v_mov_b32_e32 v27, v93
	v_lshl_add_u64 v[26:27], v[98:99], 0, v[26:27]
	v_lshlrev_b32_e32 v28, 1, v94
	v_mov_b32_e32 v29, v93
	s_waitcnt lgkmcnt(0)
	v_lshl_add_u64 v[26:27], v[26:27], 0, v[28:29]
	v_lshl_add_u64 v[34:35], v[26:27], 0, s[18:19]
	ds_read_b128 v[26:29], v119
	v_or_b32_e32 v30, v108, v118
	v_lshlrev_b32_e32 v30, 12, v30
	v_mov_b32_e32 v31, v93
	v_lshl_add_u64 v[36:37], v[34:35], 0, v[30:31]
	ds_read_b128 v[30:33], v121
	s_waitcnt lgkmcnt(1)
	global_store_dwordx4 v[36:37], v[26:29], off
	s_nop 1
	v_or_b32_e32 v26, v108, v120
	v_lshlrev_b32_e32 v26, 12, v26
	v_mov_b32_e32 v27, v93
	v_lshl_add_u64 v[26:27], v[34:35], 0, v[26:27]
	s_waitcnt lgkmcnt(0)
	global_store_dwordx4 v[26:27], v[30:33], off
	ds_read_b128 v[26:29], v123
	s_nop 0
	v_or_b32_e32 v30, v108, v122
	v_lshlrev_b32_e32 v30, 12, v30
	v_mov_b32_e32 v31, v93
	v_lshl_add_u64 v[36:37], v[34:35], 0, v[30:31]
	ds_read_b128 v[30:33], v125
	s_waitcnt lgkmcnt(1)
	global_store_dwordx4 v[36:37], v[26:29], off
	s_nop 1
	v_or_b32_e32 v26, v108, v124
	v_lshlrev_b32_e32 v26, 12, v26
	v_mov_b32_e32 v27, v93
	v_lshl_add_u64 v[26:27], v[34:35], 0, v[26:27]
	s_waitcnt lgkmcnt(0)
	global_store_dwordx4 v[26:27], v[30:33], off
	ds_read_b128 v[26:29], v127
	s_nop 0
	v_or_b32_e32 v30, v108, v126
	v_lshlrev_b32_e32 v30, 12, v30
	v_mov_b32_e32 v31, v93
	v_lshl_add_u64 v[36:37], v[34:35], 0, v[30:31]
	ds_read_b128 v[30:33], v129
	s_waitcnt lgkmcnt(1)
	global_store_dwordx4 v[36:37], v[26:29], off
	s_nop 1
	v_or_b32_e32 v26, v108, v128
	v_lshlrev_b32_e32 v26, 12, v26
	v_mov_b32_e32 v27, v93
	v_lshl_add_u64 v[26:27], v[34:35], 0, v[26:27]
	s_waitcnt lgkmcnt(0)
	global_store_dwordx4 v[26:27], v[30:33], off
	ds_read_b128 v[26:29], v131
	s_nop 0
	v_or_b32_e32 v30, v108, v130
	v_lshlrev_b32_e32 v30, 12, v30
	v_mov_b32_e32 v31, v93
	v_lshl_add_u64 v[36:37], v[34:35], 0, v[30:31]
	ds_read_b128 v[30:33], v133
	s_waitcnt lgkmcnt(1)
	global_store_dwordx4 v[36:37], v[26:29], off
	s_nop 1
	v_or_b32_e32 v26, v108, v132
	v_lshlrev_b32_e32 v26, 12, v26
	v_mov_b32_e32 v27, v93
	v_lshl_add_u64 v[26:27], v[34:35], 0, v[26:27]
	s_waitcnt lgkmcnt(0)
	global_store_dwordx4 v[26:27], v[30:33], off
	s_waitcnt lgkmcnt(0)
; __device__ __forceinline__ void p0_prologue(const Params& p, LAS unsigned char* lds, int tid) {
;     ...
;         if (r < I_DN) { p0_transpose_item(p.in[22] + (size_t)l * DFF * DM, DFF, DM, nullptr, nullptr, (bf16_t*)(wl + LO_WDN), scr, r, lane); continue; } r -= I_DN;
;         if (r < I_GLU) { p0_transpose_item(p.in[15] + (size_t)l * 1024 * 1024, 1024, 1024, nullptr, nullptr, (bf16_t*)(wl + LO_WGLU), scr, r, lane); continue; } r -= I_GLU;
.Lmy_w139:
	s_andn2_saveexec_b64 s[30:31], s[30:31]
	s_cbranch_execz .Lmy_w141
; #define LAS __attribute__((address_space(3)))
; __device__ __forceinline__ unsigned pk2(float lo, float hi) { unsigned r; asm volatile("v_cvt_pk_bf16_f32 %0, %1, %2" : "=v"(r) : "v"(lo), "v"(hi)); return r; }
; __device__ __forceinline__ void p0_transpose_item(const float* W, int K, int N, const float* gain, const float* gain2  , bf16_t* WT, LAS unsigned* scr, int item, int lane) {
;     const int nblk = N / 64, kb = item / nblk, nb = item % nblk, k0 = 64 * kb, n0 = 64 * nb;
;     if (gain2 && k0 >= 1024) gain = gain2 - 1024;
;     const int n4 = lane & 15, kq = lane >> 4;
;     f32x4 r0[8], r1[8];
;     const float* src = W + (size_t)(k0 + 2 * kq) * N + n0 + 4 * n4;
; #pragma unroll
;     for (int j = 0; j < 8; ++j) { r0[j] = __builtin_nontemporal_load((const f32x4*)(src + (size_t)(8 * j) * N)); r1[j] = __builtin_nontemporal_load((const f32x4*)(src + (size_t)(8 * j + 1) * N)); }
; #pragma unroll
;     for (int j = 0; j < 8; ++j) {
;         float g0 = 1.f, g1 = 1.f; if (gain) { g0 = gain[k0 + 8 * j + 2 * kq]; g1 = gain[k0 + 8 * j + 2 * kq + 1]; }
; #pragma unroll
;         for (int i = 0; i < 4; ++i) scr[(4 * n4 + i) * 32 + (((j ^ (n4 & 7)) << 2) | kq)] = pk2(r0[j][i] * g0, r1[j][i] * g1);
;     }
;     asm volatile("s_waitcnt lgkmcnt(0)" ::: "memory");
; #pragma unroll
;     for (int it = 0; it < 8; ++it) {
;         const int n = (lane >> 3) + 8 * it, c = lane & 7;
;         const u32x4 v = *(const LAS u32x4*)(scr + n * 32 + ((c ^ ((n >> 2) & 7)) << 2));
;         *(u32x4*)(WT + (size_t)(n0 + n) * K + k0 + 8 * c) = v;
;     }
;     asm volatile("s_waitcnt lgkmcnt(0)" ::: "memory");
; }
	v_lshlrev_b32_e32 v26, 2, v27
	v_sub_u32_e32 v26, v135, v26
	v_lshlrev_b64 v[28:29], 22, v[100:101]
	v_and_b32_e32 v100, 0x3c0, v26
	v_lshlrev_b32_e32 v26, 6, v27
	v_sub_u32_e32 v26, v134, v26
	v_lshl_add_u64 v[28:29], s[62:63], 0, v[28:29]
	v_and_b32_e32 v101, 0x3c0, v26
	v_lshl_or_b32 v26, v100, 12, v136
	v_mov_b32_e32 v27, v93
	v_lshl_add_u64 v[26:27], v[28:29], 0, v[26:27]
	v_lshlrev_b32_e32 v28, 2, v101
	v_mov_b32_e32 v29, v93
	v_lshl_add_u64 v[26:27], v[26:27], 0, v[28:29]
	v_lshl_add_u64 v[82:83], v[26:27], 0, v[92:93]
	s_movk_i32 s34, 0x1000
	v_add_co_u32_e32 v30, vcc, s34, v82
	s_mov_b32 s34, 0x9000
	s_nop 0
	v_addc_co_u32_e32 v31, vcc, 0, v83, vcc
	global_load_dwordx4 v[26:29], v[82:83], off nt
	s_nop 0
	global_load_dwordx4 v[30:33], v[30:31], off nt
	v_add_co_u32_e32 v38, vcc, s34, v82
	s_mov_b32 s34, 0x11000
	s_nop 0
	v_addc_co_u32_e32 v39, vcc, 0, v83, vcc
	global_load_dwordx4 v[34:37], v[38:39], off offset:-4096 nt
	s_nop 0
	global_load_dwordx4 v[38:41], v[38:39], off nt
	v_add_co_u32_e32 v46, vcc, s34, v82
	s_mov_b32 s34, 0x19000
	s_nop 0
	v_addc_co_u32_e32 v47, vcc, 0, v83, vcc
	global_load_dwordx4 v[42:45], v[46:47], off offset:-4096 nt
	s_nop 0
	global_load_dwordx4 v[46:49], v[46:47], off nt
	v_add_co_u32_e32 v54, vcc, s34, v82
	s_mov_b32 s34, 0x21000
	s_nop 0
	v_addc_co_u32_e32 v55, vcc, 0, v83, vcc
	global_load_dwordx4 v[50:53], v[54:55], off offset:-4096 nt
	s_waitcnt lgkmcnt(0)
	global_load_dwordx4 v[54:57], v[54:55], off nt
	v_add_co_u32_e32 v62, vcc, s34, v82
	s_mov_b32 s34, 0x29000
	s_nop 0
	v_addc_co_u32_e32 v63, vcc, 0, v83, vcc
	global_load_dwordx4 v[58:61], v[62:63], off offset:-4096 nt
	s_nop 0
	global_load_dwordx4 v[62:65], v[62:63], off nt
	v_add_co_u32_e32 v70, vcc, s34, v82
	s_mov_b32 s34, 0x31000
	s_nop 0
	v_addc_co_u32_e32 v71, vcc, 0, v83, vcc
	global_load_dwordx4 v[66:69], v[70:71], off offset:-4096 nt
	s_nop 0
	global_load_dwordx4 v[70:73], v[70:71], off nt
	v_add_co_u32_e32 v78, vcc, s34, v82
	v_add_u32_e32 v102, v95, v110
	s_nop 0
	v_addc_co_u32_e32 v79, vcc, 0, v83, vcc
	global_load_dwordx4 v[74:77], v[78:79], off offset:-4096 nt
	s_nop 0
	global_load_dwordx4 v[78:81], v[78:79], off nt
	v_add_co_u32_e32 v86, vcc, s85, v82
	v_add_u32_e32 v103, v111, v110
	s_nop 0
	v_addc_co_u32_e32 v87, vcc, 0, v83, vcc
	global_load_dwordx4 v[82:85], v[86:87], off offset:-4096 nt
	s_nop 0
	global_load_dwordx4 v[86:89], v[86:87], off nt
	v_add_u32_e32 v104, v112, v110
	v_add_u32_e32 v105, v113, v110
	v_add_u32_e32 v106, v114, v110
	s_waitcnt vmcnt(14)
	v_cvt_pk_bf16_f32 v26, v26, v30
	ds_write_b32 v102, v26
	v_cvt_pk_bf16_f32 v26, v27, v31
	ds_write_b32 v102, v26 offset:128
	v_cvt_pk_bf16_f32 v26, v28, v32
	ds_write_b32 v102, v26 offset:256
	v_cvt_pk_bf16_f32 v26, v29, v33
	ds_write_b32 v102, v26 offset:384
	s_waitcnt vmcnt(12)
	v_cvt_pk_bf16_f32 v26, v34, v38
	ds_write_b32 v103, v26
	v_cvt_pk_bf16_f32 v26, v35, v39
	ds_write_b32 v103, v26 offset:128
	v_cvt_pk_bf16_f32 v26, v36, v40
	ds_write_b32 v103, v26 offset:256
	v_cvt_pk_bf16_f32 v26, v37, v41
	ds_write_b32 v103, v26 offset:384
	s_waitcnt vmcnt(10)
	v_cvt_pk_bf16_f32 v26, v42, v46
	ds_write_b32 v104, v26
	v_cvt_pk_bf16_f32 v26, v43, v47
	ds_write_b32 v104, v26 offset:128
	v_cvt_pk_bf16_f32 v26, v44, v48
	ds_write_b32 v104, v26 offset:256
	v_cvt_pk_bf16_f32 v26, v45, v49
	ds_write_b32 v104, v26 offset:384
	s_waitcnt vmcnt(8)
	v_cvt_pk_bf16_f32 v26, v50, v54
	ds_write_b32 v105, v26
	v_cvt_pk_bf16_f32 v26, v51, v55
	ds_write_b32 v105, v26 offset:128
	v_cvt_pk_bf16_f32 v26, v52, v56
	ds_write_b32 v105, v26 offset:256
	v_cvt_pk_bf16_f32 v26, v53, v57
	ds_write_b32 v105, v26 offset:384
	s_waitcnt vmcnt(6)
	v_cvt_pk_bf16_f32 v26, v58, v62
	ds_write_b32 v106, v26
	v_cvt_pk_bf16_f32 v26, v59, v63
	ds_write_b32 v106, v26 offset:128
	v_cvt_pk_bf16_f32 v26, v60, v64
	ds_write_b32 v106, v26 offset:256
	v_cvt_pk_bf16_f32 v26, v61, v65
	ds_write_b32 v106, v26 offset:384
	s_waitcnt vmcnt(4)
	v_cvt_pk_bf16_f32 v26, v66, v70
	v_add_u32_e32 v27, v115, v110
	ds_write_b32 v27, v26
	v_cvt_pk_bf16_f32 v26, v67, v71
	ds_write_b32 v27, v26 offset:128
	v_cvt_pk_bf16_f32 v26, v68, v72
	ds_write_b32 v27, v26 offset:256
	v_cvt_pk_bf16_f32 v26, v69, v73
	ds_write_b32 v27, v26 offset:384
	s_waitcnt vmcnt(2)
	v_cvt_pk_bf16_f32 v26, v74, v78
	v_add_u32_e32 v27, v116, v110
	ds_write_b32 v27, v26
	v_cvt_pk_bf16_f32 v26, v75, v79
	ds_write_b32 v27, v26 offset:128
	v_cvt_pk_bf16_f32 v26, v76, v80
	ds_write_b32 v27, v26 offset:256
	v_cvt_pk_bf16_f32 v26, v77, v81
	ds_write_b32 v27, v26 offset:384
	s_waitcnt vmcnt(0)
	v_cvt_pk_bf16_f32 v26, v82, v86
	v_add_u32_e32 v27, v117, v110
	ds_write_b32 v27, v26
	v_cvt_pk_bf16_f32 v26, v83, v87
	ds_write_b32 v27, v26 offset:128
	v_cvt_pk_bf16_f32 v26, v84, v88
	ds_write_b32 v27, v26 offset:256
	v_cvt_pk_bf16_f32 v26, v85, v89
	ds_write_b32 v27, v26 offset:384
	v_lshlrev_b32_e32 v26, 1, v100
	v_mov_b32_e32 v27, v93
	v_lshl_add_u64 v[26:27], v[98:99], 0, v[26:27]
	v_lshlrev_b32_e32 v28, 1, v94
	v_mov_b32_e32 v29, v93
	s_waitcnt lgkmcnt(0)
	v_lshl_add_u64 v[26:27], v[26:27], 0, v[28:29]
	v_lshl_add_u64 v[34:35], v[26:27], 0, s[20:21]
	ds_read_b128 v[26:29], v119
	v_or_b32_e32 v30, v101, v118
	v_lshlrev_b32_e32 v30, 11, v30
	v_mov_b32_e32 v31, v93
	v_lshl_add_u64 v[36:37], v[34:35], 0, v[30:31]
	ds_read_b128 v[30:33], v121
	s_waitcnt lgkmcnt(1)
	global_store_dwordx4 v[36:37], v[26:29], off
	s_nop 1
	v_or_b32_e32 v26, v101, v120
	v_lshlrev_b32_e32 v26, 11, v26
	v_mov_b32_e32 v27, v93
	v_lshl_add_u64 v[26:27], v[34:35], 0, v[26:27]
	s_waitcnt lgkmcnt(0)
	global_store_dwordx4 v[26:27], v[30:33], off
	ds_read_b128 v[26:29], v123
	s_nop 0
	v_or_b32_e32 v30, v101, v122
	v_lshlrev_b32_e32 v30, 11, v30
	v_mov_b32_e32 v31, v93
	v_lshl_add_u64 v[36:37], v[34:35], 0, v[30:31]
	ds_read_b128 v[30:33], v125
	s_waitcnt lgkmcnt(1)
	global_store_dwordx4 v[36:37], v[26:29], off
	s_nop 1
	v_or_b32_e32 v26, v101, v124
	v_lshlrev_b32_e32 v26, 11, v26
	v_mov_b32_e32 v27, v93
	v_lshl_add_u64 v[26:27], v[34:35], 0, v[26:27]
	s_waitcnt lgkmcnt(0)
	global_store_dwordx4 v[26:27], v[30:33], off
	ds_read_b128 v[26:29], v127
	s_nop 0
	v_or_b32_e32 v30, v101, v126
	v_lshlrev_b32_e32 v30, 11, v30
	v_mov_b32_e32 v31, v93
	v_lshl_add_u64 v[36:37], v[34:35], 0, v[30:31]
	ds_read_b128 v[30:33], v129
	s_waitcnt lgkmcnt(1)
	global_store_dwordx4 v[36:37], v[26:29], off
	s_nop 1
	v_or_b32_e32 v26, v101, v128
	v_lshlrev_b32_e32 v26, 11, v26
	v_mov_b32_e32 v27, v93
	v_lshl_add_u64 v[26:27], v[34:35], 0, v[26:27]
	s_waitcnt lgkmcnt(0)
	global_store_dwordx4 v[26:27], v[30:33], off
	ds_read_b128 v[26:29], v131
	s_nop 0
	v_or_b32_e32 v30, v101, v130
	v_lshlrev_b32_e32 v30, 11, v30
	v_mov_b32_e32 v31, v93
	v_lshl_add_u64 v[36:37], v[34:35], 0, v[30:31]
	ds_read_b128 v[30:33], v133
	s_waitcnt lgkmcnt(1)
	global_store_dwordx4 v[36:37], v[26:29], off
	s_nop 1
	v_or_b32_e32 v26, v101, v132
	v_lshlrev_b32_e32 v26, 11, v26
	v_mov_b32_e32 v27, v93
	v_lshl_add_u64 v[26:27], v[34:35], 0, v[26:27]
	s_waitcnt lgkmcnt(0)
	global_store_dwordx4 v[26:27], v[30:33], off
	s_waitcnt lgkmcnt(0)

; __device__ __forceinline__ void p0_transpose_item(const float* W, int K, int N, const float* gain, const float* gain2  , bf16_t* WT, LAS unsigned* scr, int item, int lane) {
;     const int nblk = N / 64, kb = item / nblk, nb = item % nblk, k0 = 64 * kb, n0 = 64 * nb;
;     if (gain2 && k0 >= 1024) gain = gain2 - 1024;
;     const int n4 = lane & 15, kq = lane >> 4;
;     f32x4 r0[8], r1[8];
;     const float* src = W + (size_t)(k0 + 2 * kq) * N + n0 + 4 * n4;
; #pragma unroll
;     for (int j = 0; j < 8; ++j) { r0[j] = __builtin_nontemporal_load((const f32x4*)(src + (size_t)(8 * j) * N)); r1[j] = __builtin_nontemporal_load((const f32x4*)(src + (size_t)(8 * j + 1) * N)); }
.Lmy_w142:
	s_andn2_saveexec_b64 s[28:29], s[28:29]
	s_cbranch_execz .Lmy_w144
	v_add_u32_e32 v26, 0xeb00, v26
	v_lshlrev_b64 v[28:29], 26, v[100:101]
	v_readlane_b32 s40, v253, 18
	v_bfe_u32 v100, v26, 5, 11
	v_lshlrev_b32_e32 v26, 6, v27
	v_readlane_b32 s52, v253, 30
	v_readlane_b32 s53, v253, 31
	v_sub_u32_e32 v26, v134, v26
	v_and_b32_e32 v101, 0x7c0, v26
	v_lshl_add_u64 v[28:29], s[52:53], 0, v[28:29]
	v_lshl_or_b32 v26, v100, 19, v137
	v_mov_b32_e32 v27, v93
	v_lshl_add_u64 v[26:27], v[28:29], 0, v[26:27]
	v_lshlrev_b32_e32 v28, 2, v101
	v_mov_b32_e32 v29, v93
	v_lshl_add_u64 v[26:27], v[26:27], 0, v[28:29]
	v_lshl_add_u64 v[82:83], v[26:27], 0, v[92:93]
	v_add_co_u32_e32 v30, vcc, s37, v82
	s_mov_b32 s30, 0x72000
	s_nop 0
	v_addc_co_u32_e32 v31, vcc, 0, v83, vcc
	global_load_dwordx4 v[26:29], v[82:83], off nt
	s_nop 0
	global_load_dwordx4 v[30:33], v[30:31], off nt
	v_add_co_u32_e32 v34, vcc, s38, v82
	v_readlane_b32 s41, v253, 19
	s_nop 0
	v_addc_co_u32_e32 v35, vcc, 0, v83, vcc
	v_add_co_u32_e32 v38, vcc, s39, v82
	v_readlane_b32 s42, v253, 20
	s_nop 0
	v_addc_co_u32_e32 v39, vcc, 0, v83, vcc
	global_load_dwordx4 v[34:37], v[34:35], off nt
	s_nop 0
	global_load_dwordx4 v[38:41], v[38:39], off nt
	v_add_co_u32_e32 v42, vcc, s2, v82
	v_readlane_b32 s43, v253, 21
	s_nop 0
	v_addc_co_u32_e32 v43, vcc, 0, v83, vcc
	v_add_co_u32_e32 v46, vcc, s3, v82
	v_readlane_b32 s44, v253, 22
	s_nop 0
	v_addc_co_u32_e32 v47, vcc, 0, v83, vcc
	global_load_dwordx4 v[42:45], v[42:43], off nt
	s_nop 0
	global_load_dwordx4 v[46:49], v[46:47], off nt
	v_add_co_u32_e32 v50, vcc, s76, v82
	v_readlane_b32 s45, v253, 23
	s_nop 0
	v_addc_co_u32_e32 v51, vcc, 0, v83, vcc
	v_add_co_u32_e32 v54, vcc, s77, v82
	v_readlane_b32 s46, v253, 24
	s_nop 0
	v_addc_co_u32_e32 v55, vcc, 0, v83, vcc
	global_load_dwordx4 v[50:53], v[50:51], off nt
	s_waitcnt lgkmcnt(0)
	global_load_dwordx4 v[54:57], v[54:55], off nt
	v_add_co_u32_e32 v58, vcc, s78, v82
	v_readlane_b32 s47, v253, 25
	s_nop 0
	v_addc_co_u32_e32 v59, vcc, 0, v83, vcc
	v_add_co_u32_e32 v62, vcc, s79, v82
	v_readlane_b32 s48, v253, 26
	s_nop 0
	v_addc_co_u32_e32 v63, vcc, 0, v83, vcc
	global_load_dwordx4 v[58:61], v[58:59], off nt
	s_nop 0
	global_load_dwordx4 v[62:65], v[62:63], off nt
	v_add_co_u32_e32 v66, vcc, s80, v82
	v_readlane_b32 s49, v253, 27
	s_nop 0
	v_addc_co_u32_e32 v67, vcc, 0, v83, vcc
	v_add_co_u32_e32 v70, vcc, s81, v82
	v_readlane_b32 s50, v253, 28
	s_nop 0
	v_addc_co_u32_e32 v71, vcc, 0, v83, vcc
	global_load_dwordx4 v[66:69], v[66:67], off nt
	s_nop 0
	global_load_dwordx4 v[70:73], v[70:71], off nt
	v_add_co_u32_e32 v74, vcc, s82, v82
	v_readlane_b32 s51, v253, 29
	s_nop 0
	v_addc_co_u32_e32 v75, vcc, 0, v83, vcc
	v_add_co_u32_e32 v78, vcc, s83, v82
	v_readlane_b32 s54, v253, 32
	s_nop 0
	v_addc_co_u32_e32 v79, vcc, 0, v83, vcc
	global_load_dwordx4 v[74:77], v[74:75], off nt
	s_nop 0
	global_load_dwordx4 v[78:81], v[78:79], off nt
	v_add_co_u32_e32 v84, vcc, s84, v82
	v_readlane_b32 s55, v253, 33
	s_nop 0
	v_addc_co_u32_e32 v85, vcc, 0, v83, vcc
	v_add_co_u32_e32 v86, vcc, s30, v82
	s_nop 1
	v_addc_co_u32_e32 v87, vcc, 0, v83, vcc
	global_load_dwordx4 v[82:85], v[84:85], off nt
	s_nop 0
	global_load_dwordx4 v[86:89], v[86:87], off nt
	s_waitcnt vmcnt(14)
	v_cvt_pk_bf16_f32 v26, v26, v30
	v_add_u32_e32 v30, v95, v110
	ds_write_b32 v30, v26
	v_cvt_pk_bf16_f32 v26, v27, v31
	ds_write_b32 v30, v26 offset:128
	v_cvt_pk_bf16_f32 v26, v28, v32
	ds_write_b32 v30, v26 offset:256
	v_cvt_pk_bf16_f32 v26, v29, v33
	ds_write_b32 v30, v26 offset:384
	s_waitcnt vmcnt(12)
	v_cvt_pk_bf16_f32 v26, v34, v38
	v_add_u32_e32 v27, v111, v110
	ds_write_b32 v27, v26
	v_cvt_pk_bf16_f32 v26, v35, v39
	ds_write_b32 v27, v26 offset:128
	v_cvt_pk_bf16_f32 v26, v36, v40
	ds_write_b32 v27, v26 offset:256
	v_cvt_pk_bf16_f32 v26, v37, v41
	ds_write_b32 v27, v26 offset:384
	s_waitcnt vmcnt(10)
; #define LAS __attribute__((address_space(3)))
; __device__ __forceinline__ unsigned pk2(float lo, float hi) { unsigned r; asm volatile("v_cvt_pk_bf16_f32 %0, %1, %2" : "=v"(r) : "v"(lo), "v"(hi)); return r; }
; __device__ __forceinline__ void p0_transpose_item(const float* W, int K, int N, const float* gain, const float* gain2  , bf16_t* WT, LAS unsigned* scr, int item, int lane) {
;     ...
;     for (int j = 0; j < 8; ++j) {
;         float g0 = 1.f, g1 = 1.f; if (gain) { g0 = gain[k0 + 8 * j + 2 * kq]; g1 = gain[k0 + 8 * j + 2 * kq + 1]; }
; #pragma unroll
;         for (int i = 0; i < 4; ++i) scr[(4 * n4 + i) * 32 + (((j ^ (n4 & 7)) << 2) | kq)] = pk2(r0[j][i] * g0, r1[j][i] * g1);
;     }
;     asm volatile("s_waitcnt lgkmcnt(0)" ::: "memory");
; #pragma unroll
;     for (int it = 0; it < 8; ++it) {
;         const int n = (lane >> 3) + 8 * it, c = lane & 7;
;         const u32x4 v = *(const LAS u32x4*)(scr + n * 32 + ((c ^ ((n >> 2) & 7)) << 2));
;         *(u32x4*)(WT + (size_t)(n0 + n) * K + k0 + 8 * c) = v;
;     }
;     asm volatile("s_waitcnt lgkmcnt(0)" ::: "memory");
; }
	v_cvt_pk_bf16_f32 v26, v42, v46
	v_add_u32_e32 v27, v112, v110
	ds_write_b32 v27, v26
	v_cvt_pk_bf16_f32 v26, v43, v47
	ds_write_b32 v27, v26 offset:128
	v_cvt_pk_bf16_f32 v26, v44, v48
	ds_write_b32 v27, v26 offset:256
	v_cvt_pk_bf16_f32 v26, v45, v49
	ds_write_b32 v27, v26 offset:384
	s_waitcnt vmcnt(8)
	v_cvt_pk_bf16_f32 v26, v50, v54
	v_add_u32_e32 v27, v113, v110
	ds_write_b32 v27, v26
	v_cvt_pk_bf16_f32 v26, v51, v55
	ds_write_b32 v27, v26 offset:128
	v_cvt_pk_bf16_f32 v26, v52, v56
	ds_write_b32 v27, v26 offset:256
	v_cvt_pk_bf16_f32 v26, v53, v57
	ds_write_b32 v27, v26 offset:384
	s_waitcnt vmcnt(6)
	v_cvt_pk_bf16_f32 v26, v58, v62
	v_add_u32_e32 v27, v114, v110
	ds_write_b32 v27, v26
	v_cvt_pk_bf16_f32 v26, v59, v63
	ds_write_b32 v27, v26 offset:128
	v_cvt_pk_bf16_f32 v26, v60, v64
	ds_write_b32 v27, v26 offset:256
	v_cvt_pk_bf16_f32 v26, v61, v65
	ds_write_b32 v27, v26 offset:384
	s_waitcnt vmcnt(4)
	v_cvt_pk_bf16_f32 v26, v66, v70
	v_add_u32_e32 v27, v115, v110
	ds_write_b32 v27, v26
	v_cvt_pk_bf16_f32 v26, v67, v71
	ds_write_b32 v27, v26 offset:128
	v_cvt_pk_bf16_f32 v26, v68, v72
	ds_write_b32 v27, v26 offset:256
	v_cvt_pk_bf16_f32 v26, v69, v73
	ds_write_b32 v27, v26 offset:384
	s_waitcnt vmcnt(2)
	v_cvt_pk_bf16_f32 v26, v74, v78
	v_add_u32_e32 v27, v116, v110
	ds_write_b32 v27, v26
	v_cvt_pk_bf16_f32 v26, v75, v79
	ds_write_b32 v27, v26 offset:128
	v_cvt_pk_bf16_f32 v26, v76, v80
	ds_write_b32 v27, v26 offset:256
	v_cvt_pk_bf16_f32 v26, v77, v81
	ds_write_b32 v27, v26 offset:384
	s_waitcnt vmcnt(0)
	v_cvt_pk_bf16_f32 v26, v82, v86
	v_add_u32_e32 v27, v117, v110
	ds_write_b32 v27, v26
	v_cvt_pk_bf16_f32 v26, v83, v87
	ds_write_b32 v27, v26 offset:128
	v_cvt_pk_bf16_f32 v26, v84, v88
	ds_write_b32 v27, v26 offset:256
	v_cvt_pk_bf16_f32 v26, v85, v89
	ds_write_b32 v27, v26 offset:384
	v_lshlrev_b32_e32 v26, 7, v100
	v_mov_b32_e32 v27, v93
	v_lshl_add_u64 v[26:27], v[98:99], 0, v[26:27]
	v_lshlrev_b32_e32 v28, 1, v94
	v_mov_b32_e32 v29, v93
	s_waitcnt lgkmcnt(0)
	v_lshl_add_u64 v[26:27], v[26:27], 0, v[28:29]
	v_lshl_add_u64 v[34:35], v[26:27], 0, s[22:23]
	ds_read_b128 v[26:29], v119
	v_or_b32_e32 v30, v101, v118
	v_lshlrev_b32_e32 v30, 14, v30
	v_mov_b32_e32 v31, v93
	v_lshl_add_u64 v[36:37], v[34:35], 0, v[30:31]
	ds_read_b128 v[30:33], v121
	s_waitcnt lgkmcnt(1)
	global_store_dwordx4 v[36:37], v[26:29], off
	s_nop 1
	v_or_b32_e32 v26, v101, v120
	v_lshlrev_b32_e32 v26, 14, v26
	v_mov_b32_e32 v27, v93
	v_lshl_add_u64 v[26:27], v[34:35], 0, v[26:27]
	s_waitcnt lgkmcnt(0)
	global_store_dwordx4 v[26:27], v[30:33], off
	ds_read_b128 v[26:29], v123
	s_nop 0
	v_or_b32_e32 v30, v101, v122
	v_lshlrev_b32_e32 v30, 14, v30
	v_mov_b32_e32 v31, v93
	v_lshl_add_u64 v[36:37], v[34:35], 0, v[30:31]
	ds_read_b128 v[30:33], v125
	s_waitcnt lgkmcnt(1)
	global_store_dwordx4 v[36:37], v[26:29], off
	s_nop 1
	v_or_b32_e32 v26, v101, v124
	v_lshlrev_b32_e32 v26, 14, v26
	v_mov_b32_e32 v27, v93
	v_lshl_add_u64 v[26:27], v[34:35], 0, v[26:27]
	s_waitcnt lgkmcnt(0)
	global_store_dwordx4 v[26:27], v[30:33], off
	ds_read_b128 v[26:29], v127
	s_nop 0
	v_or_b32_e32 v30, v101, v126
	v_lshlrev_b32_e32 v30, 14, v30
	v_mov_b32_e32 v31, v93
	v_lshl_add_u64 v[36:37], v[34:35], 0, v[30:31]
	ds_read_b128 v[30:33], v129
	s_waitcnt lgkmcnt(1)
	global_store_dwordx4 v[36:37], v[26:29], off
	s_nop 1
	v_or_b32_e32 v26, v101, v128
	v_lshlrev_b32_e32 v26, 14, v26
	v_mov_b32_e32 v27, v93
	v_lshl_add_u64 v[26:27], v[34:35], 0, v[26:27]
	s_waitcnt lgkmcnt(0)
	global_store_dwordx4 v[26:27], v[30:33], off
	ds_read_b128 v[26:29], v131
	s_nop 0
	v_or_b32_e32 v30, v101, v130
	v_lshlrev_b32_e32 v30, 14, v30
	v_mov_b32_e32 v31, v93
	v_lshl_add_u64 v[36:37], v[34:35], 0, v[30:31]
	ds_read_b128 v[30:33], v133
	s_waitcnt lgkmcnt(1)
	global_store_dwordx4 v[36:37], v[26:29], off
	s_nop 1
	v_or_b32_e32 v26, v101, v132
	v_lshlrev_b32_e32 v26, 14, v26
	v_mov_b32_e32 v27, v93
	v_lshl_add_u64 v[26:27], v[34:35], 0, v[26:27]
	s_waitcnt lgkmcnt(0)
	global_store_dwordx4 v[26:27], v[30:33], off
	s_waitcnt lgkmcnt(0)

; __device__ __forceinline__ unsigned pk2(float lo, float hi) { unsigned r; asm volatile("v_cvt_pk_bf16_f32 %0, %1, %2" : "=v"(r) : "v"(lo), "v"(hi)); return r; }
; __device__ __forceinline__ void p0_transpose_item(const float* W, int K, int N, const float* gain, const float* gain2  , bf16_t* WT, LAS unsigned* scr, int item, int lane) {
;     const int nblk = N / 64, kb = item / nblk, nb = item % nblk, k0 = 64 * kb, n0 = 64 * nb;
;     if (gain2 && k0 >= 1024) gain = gain2 - 1024;
;     const int n4 = lane & 15, kq = lane >> 4;
;     f32x4 r0[8], r1[8];
;     const float* src = W + (size_t)(k0 + 2 * kq) * N + n0 + 4 * n4;
; #pragma unroll
;     for (int j = 0; j < 8; ++j) { r0[j] = __builtin_nontemporal_load((const f32x4*)(src + (size_t)(8 * j) * N)); r1[j] = __builtin_nontemporal_load((const f32x4*)(src + (size_t)(8 * j + 1) * N)); }
; #pragma unroll
;     for (int j = 0; j < 8; ++j) {
;         float g0 = 1.f, g1 = 1.f; if (gain) { g0 = gain[k0 + 8 * j + 2 * kq]; g1 = gain[k0 + 8 * j + 2 * kq + 1]; }
; #pragma unroll
;         for (int i = 0; i < 4; ++i) scr[(4 * n4 + i) * 32 + (((j ^ (n4 & 7)) << 2) | kq)] = pk2(r0[j][i] * g0, r1[j][i] * g1);
.Lmy_w145:
	s_andn2_saveexec_b64 s[28:29], s[0:1]
	s_cbranch_execz .Lmy_w163
	v_add_u32_e32 v26, 0xfb00, v26
	v_lshrrev_b32_e32 v26, 1, v26
	v_readlane_b32 s40, v253, 18
	v_and_b32_e32 v109, 0x7fc0, v26
	v_lshlrev_b32_e32 v26, 6, v27
	v_lshlrev_b64 v[28:29], 26, v[100:101]
	v_readlane_b32 s50, v253, 28
	v_readlane_b32 s51, v253, 29
	v_sub_u32_e32 v26, v134, v26
	v_or_b32_e32 v102, v109, v91
	v_lshl_add_u64 v[28:29], s[50:51], 0, v[28:29]
	v_and_b32_e32 v108, 0x1fc0, v26
	v_lshlrev_b32_e32 v26, 15, v102
	v_mov_b32_e32 v27, v93
	v_lshl_add_u64 v[26:27], v[28:29], 0, v[26:27]
	v_lshlrev_b32_e32 v28, 2, v108
	v_mov_b32_e32 v29, v93
	v_lshl_add_u64 v[26:27], v[26:27], 0, v[28:29]
	v_lshl_add_u64 v[26:27], v[26:27], 0, v[92:93]
	s_mov_b32 s0, 0x8000
	v_add_co_u32_e32 v28, vcc, s0, v26
	v_lshlrev_b32_e32 v100, 11, v100
	s_nop 0
	v_addc_co_u32_e32 v29, vcc, 0, v27, vcc
	global_load_dwordx4 v[82:85], v[26:27], off nt
	global_load_dwordx4 v[86:89], v[28:29], off nt
	v_add_co_u32_e32 v28, vcc, s78, v26
	v_readlane_b32 s48, v253, 26
	s_nop 0
	v_addc_co_u32_e32 v29, vcc, 0, v27, vcc
	v_add_co_u32_e32 v30, vcc, s86, v26
	v_readlane_b32 s49, v253, 27
	s_nop 0
	v_addc_co_u32_e32 v31, vcc, 0, v27, vcc
	global_load_dwordx4 v[74:77], v[28:29], off nt
	global_load_dwordx4 v[78:81], v[30:31], off nt
	v_add_co_u32_e32 v28, vcc, s87, v26
	v_ashrrev_i32_e32 v101, 31, v100
	s_nop 0
	v_addc_co_u32_e32 v29, vcc, 0, v27, vcc
	v_add_co_u32_e32 v30, vcc, s88, v26
	v_cndmask_b32_e64 v103, 0, 1, s[8:9]
	s_nop 0
	v_addc_co_u32_e32 v31, vcc, 0, v27, vcc
	global_load_dwordx4 v[66:69], v[28:29], off nt
	global_load_dwordx4 v[70:73], v[30:31], off nt
	v_add_co_u32_e32 v28, vcc, s89, v26
	v_lshl_add_u64 v[100:101], v[100:101], 2, s[48:49]
	s_nop 0
	v_addc_co_u32_e32 v29, vcc, 0, v27, vcc
	v_add_co_u32_e32 v30, vcc, s56, v26
	v_mov_b32_e32 v104, 1.0
	s_nop 0
	v_addc_co_u32_e32 v31, vcc, 0, v27, vcc
	global_load_dwordx4 v[58:61], v[28:29], off nt
	global_load_dwordx4 v[62:65], v[30:31], off nt
	v_add_co_u32_e32 v28, vcc, s57, v26
	v_cmp_ne_u32_e64 s[0:1], 1, v103
	s_nop 0
	v_addc_co_u32_e32 v29, vcc, 0, v27, vcc
	v_add_co_u32_e32 v30, vcc, s58, v26
	v_lshlrev_b32_e32 v102, 2, v102
	s_nop 0
	v_addc_co_u32_e32 v31, vcc, 0, v27, vcc
	global_load_dwordx4 v[50:53], v[28:29], off nt
	s_waitcnt lgkmcnt(0)
	global_load_dwordx4 v[54:57], v[30:31], off nt
	v_add_co_u32_e32 v28, vcc, s59, v26
	v_mov_b32_e32 v106, 1.0
	s_nop 0
	v_addc_co_u32_e32 v29, vcc, 0, v27, vcc
	v_add_co_u32_e32 v30, vcc, s60, v26
	v_mov_b32_e32 v107, 1.0
	s_nop 0
	v_addc_co_u32_e32 v31, vcc, 0, v27, vcc
	global_load_dwordx4 v[42:45], v[28:29], off nt
	global_load_dwordx4 v[46:49], v[30:31], off nt
	v_add_co_u32_e32 v28, vcc, s61, v26
	v_readlane_b32 s41, v253, 19
	s_nop 0
	v_addc_co_u32_e32 v29, vcc, 0, v27, vcc
	v_add_co_u32_e32 v30, vcc, 0x188000, v26
	v_readlane_b32 s42, v253, 20
	s_nop 0
	v_addc_co_u32_e32 v31, vcc, 0, v27, vcc
	global_load_dwordx4 v[34:37], v[28:29], off nt
	global_load_dwordx4 v[38:41], v[30:31], off nt
	v_add_co_u32_e32 v28, vcc, 0x1c0000, v26
	v_readlane_b32 s43, v253, 21
	s_nop 0
	v_addc_co_u32_e32 v29, vcc, 0, v27, vcc
	v_add_co_u32_e32 v30, vcc, 0x1c8000, v26
	v_readlane_b32 s44, v253, 22
	s_nop 0
	v_addc_co_u32_e32 v31, vcc, 0, v27, vcc
	global_load_dwordx4 v[26:29], v[28:29], off nt
	s_nop 0
	global_load_dwordx4 v[30:33], v[30:31], off nt
	s_andn2_b64 vcc, exec, s[8:9]
	v_readlane_b32 s45, v253, 23
	v_readlane_b32 s46, v253, 24
	v_readlane_b32 s47, v253, 25
	v_readlane_b32 s52, v253, 30
	v_readlane_b32 s53, v253, 31
	v_readlane_b32 s54, v253, 32
	v_readlane_b32 s55, v253, 33
	s_cbranch_vccnz .Lmy_w148
	v_mov_b32_e32 v103, v93
	v_lshl_add_u64 v[106:107], v[100:101], 0, v[102:103]
	global_load_dwordx2 v[106:107], v[106:107], off
.Lmy_w148:
	s_waitcnt vmcnt(0)
	v_mul_f32_e32 v82, v82, v106
	v_mul_f32_e32 v86, v86, v107
	v_cvt_pk_bf16_f32 v82, v82, v86
	v_add_u32_e32 v86, v95, v110
	ds_write_b32 v86, v82
	v_mul_f32_e32 v82, v83, v106
	v_mul_f32_e32 v83, v87, v107
	v_cvt_pk_bf16_f32 v82, v82, v83
	ds_write_b32 v86, v82 offset:128
	v_mul_f32_e32 v82, v84, v106
	v_mul_f32_e32 v83, v88, v107
	v_cvt_pk_bf16_f32 v82, v82, v83
	ds_write_b32 v86, v82 offset:256
	v_mul_f32_e32 v82, v85, v106
	s_and_b64 vcc, exec, s[0:1]
	v_mov_b32_e32 v105, 1.0
	v_mul_f32_e32 v83, v89, v107
	v_cvt_pk_bf16_f32 v82, v82, v83
	ds_write_b32 v86, v82 offset:384
	s_cbranch_vccnz .Lmy_w150
	v_mov_b32_e32 v103, v93
	v_lshl_add_u64 v[82:83], v[100:101], 0, v[102:103]
	global_load_dwordx2 v[104:105], v[82:83], off offset:32
.Lmy_w150:
	s_waitcnt vmcnt(0)
	v_mul_f32_e32 v74, v74, v104
	v_mul_f32_e32 v78, v78, v105
	v_cvt_pk_bf16_f32 v74, v74, v78
	v_add_u32_e32 v78, v111, v110
	ds_write_b32 v78, v74
	v_mul_f32_e32 v74, v75, v104
	v_mul_f32_e32 v75, v79, v105
	v_cvt_pk_bf16_f32 v74, v74, v75
	ds_write_b32 v78, v74 offset:128
	v_mul_f32_e32 v74, v76, v104
	v_mul_f32_e32 v75, v80, v105
	v_cvt_pk_bf16_f32 v74, v74, v75
	ds_write_b32 v78, v74 offset:256
	v_mul_f32_e32 v74, v77, v104
	v_mul_f32_e32 v75, v81, v105
	v_cvt_pk_bf16_f32 v74, v74, v75
	ds_write_b32 v78, v74 offset:384
	v_mov_b32_e32 v74, 1.0
	s_and_b64 vcc, exec, s[0:1]
	v_mov_b32_e32 v76, 1.0
	v_mov_b32_e32 v77, 1.0
	s_cbranch_vccnz .Lmy_w152
	v_mov_b32_e32 v103, v93
	v_lshl_add_u64 v[76:77], v[100:101], 0, v[102:103]
	global_load_dwordx2 v[76:77], v[76:77], off offset:64
; #define LAS __attribute__((address_space(3)))
; __device__ __forceinline__ unsigned pk2(float lo, float hi) { unsigned r; asm volatile("v_cvt_pk_bf16_f32 %0, %1, %2" : "=v"(r) : "v"(lo), "v"(hi)); return r; }
; __device__ __forceinline__ void p0_transpose_item(const float* W, int K, int N, const float* gain, const float* gain2  , bf16_t* WT, LAS unsigned* scr, int item, int lane) {
;     ...
;     for (int j = 0; j < 8; ++j) {
;         float g0 = 1.f, g1 = 1.f; if (gain) { g0 = gain[k0 + 8 * j + 2 * kq]; g1 = gain[k0 + 8 * j + 2 * kq + 1]; }
; #pragma unroll
;         for (int i = 0; i < 4; ++i) scr[(4 * n4 + i) * 32 + (((j ^ (n4 & 7)) << 2) | kq)] = pk2(r0[j][i] * g0, r1[j][i] * g1);
;     }
;     asm volatile("s_waitcnt lgkmcnt(0)" ::: "memory");
; #pragma unroll
;     for (int it = 0; it < 8; ++it) {
;         const int n = (lane >> 3) + 8 * it, c = lane & 7;
;         const u32x4 v = *(const LAS u32x4*)(scr + n * 32 + ((c ^ ((n >> 2) & 7)) << 2));
;         *(u32x4*)(WT + (size_t)(n0 + n) * K + k0 + 8 * c) = v;
;     }
;     asm volatile("s_waitcnt lgkmcnt(0)" ::: "memory");
; }
.Lmy_w152:
	s_waitcnt vmcnt(0)
	v_mul_f32_e32 v66, v66, v76
	v_mul_f32_e32 v70, v70, v77
	v_cvt_pk_bf16_f32 v66, v66, v70
	v_add_u32_e32 v70, v112, v110
	ds_write_b32 v70, v66
	v_mul_f32_e32 v66, v67, v76
	v_mul_f32_e32 v67, v71, v77
	v_cvt_pk_bf16_f32 v66, v66, v67
	ds_write_b32 v70, v66 offset:128
	v_mul_f32_e32 v66, v68, v76
	v_mul_f32_e32 v67, v72, v77
	v_cvt_pk_bf16_f32 v66, v66, v67
	ds_write_b32 v70, v66 offset:256
	v_mul_f32_e32 v66, v69, v76
	s_and_b64 vcc, exec, s[0:1]
	v_mov_b32_e32 v75, 1.0
	v_mul_f32_e32 v67, v73, v77
	v_cvt_pk_bf16_f32 v66, v66, v67
	ds_write_b32 v70, v66 offset:384
	s_cbranch_vccnz .Lmy_w154
	v_mov_b32_e32 v103, v93
	v_lshl_add_u64 v[66:67], v[100:101], 0, v[102:103]
	global_load_dwordx2 v[74:75], v[66:67], off offset:96
.Lmy_w154:
	s_waitcnt vmcnt(0)
	v_mul_f32_e32 v58, v58, v74
	v_mul_f32_e32 v62, v62, v75
	v_cvt_pk_bf16_f32 v58, v58, v62
	v_add_u32_e32 v62, v113, v110
	ds_write_b32 v62, v58
	v_mul_f32_e32 v58, v59, v74
	v_mul_f32_e32 v59, v63, v75
	v_cvt_pk_bf16_f32 v58, v58, v59
	ds_write_b32 v62, v58 offset:128
	v_mul_f32_e32 v58, v60, v74
	v_mul_f32_e32 v59, v64, v75
	v_cvt_pk_bf16_f32 v58, v58, v59
	ds_write_b32 v62, v58 offset:256
	v_mul_f32_e32 v58, v61, v74
	v_mul_f32_e32 v59, v65, v75
	v_cvt_pk_bf16_f32 v58, v58, v59
	ds_write_b32 v62, v58 offset:384
	v_mov_b32_e32 v58, 1.0
	s_and_b64 vcc, exec, s[0:1]
	v_mov_b32_e32 v60, 1.0
	v_mov_b32_e32 v61, 1.0
	s_cbranch_vccnz .Lmy_w156
	v_mov_b32_e32 v103, v93
	v_lshl_add_u64 v[60:61], v[100:101], 0, v[102:103]
	global_load_dwordx2 v[60:61], v[60:61], off offset:128
.Lmy_w156:
	s_waitcnt vmcnt(0)
	v_mul_f32_e32 v50, v50, v60
	v_mul_f32_e32 v54, v54, v61
	v_cvt_pk_bf16_f32 v50, v50, v54
	v_add_u32_e32 v54, v114, v110
	ds_write_b32 v54, v50
	v_mul_f32_e32 v50, v51, v60
	v_mul_f32_e32 v51, v55, v61
	v_cvt_pk_bf16_f32 v50, v50, v51
	ds_write_b32 v54, v50 offset:128
	v_mul_f32_e32 v50, v52, v60
	v_mul_f32_e32 v51, v56, v61
	v_cvt_pk_bf16_f32 v50, v50, v51
	ds_write_b32 v54, v50 offset:256
	v_mul_f32_e32 v50, v53, v60
	s_and_b64 vcc, exec, s[0:1]
	v_mov_b32_e32 v59, 1.0
	v_mul_f32_e32 v51, v57, v61
	v_cvt_pk_bf16_f32 v50, v50, v51
	ds_write_b32 v54, v50 offset:384
	s_cbranch_vccnz .Lmy_w158
	v_mov_b32_e32 v103, v93
	v_lshl_add_u64 v[50:51], v[100:101], 0, v[102:103]
	global_load_dwordx2 v[58:59], v[50:51], off offset:160
.Lmy_w158:
	s_waitcnt vmcnt(0)
	v_mul_f32_e32 v42, v42, v58
	v_mul_f32_e32 v46, v46, v59
	v_cvt_pk_bf16_f32 v42, v42, v46
	v_add_u32_e32 v46, v115, v110
	ds_write_b32 v46, v42
	v_mul_f32_e32 v42, v43, v58
	v_mul_f32_e32 v43, v47, v59
	v_cvt_pk_bf16_f32 v42, v42, v43
	ds_write_b32 v46, v42 offset:128
	v_mul_f32_e32 v42, v44, v58
	v_mul_f32_e32 v43, v48, v59
	v_cvt_pk_bf16_f32 v42, v42, v43
	ds_write_b32 v46, v42 offset:256
	v_mul_f32_e32 v42, v45, v58
	v_mul_f32_e32 v43, v49, v59
	v_cvt_pk_bf16_f32 v42, v42, v43
	ds_write_b32 v46, v42 offset:384
	v_mov_b32_e32 v42, 1.0
	s_and_b64 vcc, exec, s[0:1]
	v_mov_b32_e32 v44, 1.0
	v_mov_b32_e32 v45, 1.0
	s_cbranch_vccnz .Lmy_w160
	v_mov_b32_e32 v103, v93
	v_lshl_add_u64 v[44:45], v[100:101], 0, v[102:103]
	global_load_dwordx2 v[44:45], v[44:45], off offset:192
.Lmy_w160:
	s_waitcnt vmcnt(0)
	v_mul_f32_e32 v34, v34, v44
	v_mul_f32_e32 v38, v38, v45
	v_cvt_pk_bf16_f32 v34, v34, v38
	v_add_u32_e32 v38, v116, v110
	ds_write_b32 v38, v34
	v_mul_f32_e32 v34, v35, v44
	v_mul_f32_e32 v35, v39, v45
	v_cvt_pk_bf16_f32 v34, v34, v35
	ds_write_b32 v38, v34 offset:128
	v_mul_f32_e32 v34, v36, v44
	v_mul_f32_e32 v35, v40, v45
	v_cvt_pk_bf16_f32 v34, v34, v35
	ds_write_b32 v38, v34 offset:256
	v_mul_f32_e32 v34, v37, v44
	s_and_b64 vcc, exec, s[0:1]
	v_mov_b32_e32 v43, 1.0
	v_mul_f32_e32 v35, v41, v45
	v_cvt_pk_bf16_f32 v34, v34, v35
	ds_write_b32 v38, v34 offset:384
	s_cbranch_vccnz .Lmy_w162
	v_mov_b32_e32 v103, v93
	v_lshl_add_u64 v[34:35], v[100:101], 0, v[102:103]
	global_load_dwordx2 v[42:43], v[34:35], off offset:224
.Lmy_w162:
	s_waitcnt vmcnt(0)
	v_mul_f32_e32 v26, v26, v42
	v_mul_f32_e32 v30, v30, v43
	v_cvt_pk_bf16_f32 v26, v26, v30
	v_add_u32_e32 v30, v117, v110
	ds_write_b32 v30, v26
	v_mul_f32_e32 v26, v27, v42
	v_mul_f32_e32 v27, v31, v43
	v_cvt_pk_bf16_f32 v26, v26, v27
	ds_write_b32 v30, v26 offset:128
	v_mul_f32_e32 v26, v28, v42
	v_mul_f32_e32 v27, v32, v43
	v_cvt_pk_bf16_f32 v26, v26, v27
	ds_write_b32 v30, v26 offset:256
	v_mul_f32_e32 v26, v29, v42
	v_mul_f32_e32 v27, v33, v43
	v_cvt_pk_bf16_f32 v26, v26, v27
	ds_write_b32 v30, v26 offset:384
	v_lshlrev_b32_e32 v26, 1, v109
	v_mov_b32_e32 v27, v93
	v_lshl_add_u64 v[26:27], v[98:99], 0, v[26:27]
	v_lshlrev_b32_e32 v28, 1, v94
	v_mov_b32_e32 v29, v93
	s_waitcnt lgkmcnt(0)
	v_lshl_add_u64 v[26:27], v[26:27], 0, v[28:29]
	v_lshl_add_u64 v[34:35], v[26:27], 0, s[24:25]
	ds_read_b128 v[26:29], v119
	v_or_b32_e32 v30, v108, v118
	v_lshlrev_b32_e32 v30, 12, v30
	v_mov_b32_e32 v31, v93
	v_lshl_add_u64 v[36:37], v[34:35], 0, v[30:31]
	ds_read_b128 v[30:33], v121
	s_waitcnt lgkmcnt(1)
	global_store_dwordx4 v[36:37], v[26:29], off
	s_nop 1
	v_or_b32_e32 v26, v108, v120
	v_lshlrev_b32_e32 v26, 12, v26
	v_mov_b32_e32 v27, v93
	v_lshl_add_u64 v[26:27], v[34:35], 0, v[26:27]
	s_waitcnt lgkmcnt(0)
	global_store_dwordx4 v[26:27], v[30:33], off
	ds_read_b128 v[26:29], v123
	s_nop 0
	v_or_b32_e32 v30, v108, v122
	v_lshlrev_b32_e32 v30, 12, v30
	v_mov_b32_e32 v31, v93
	v_lshl_add_u64 v[36:37], v[34:35], 0, v[30:31]
	ds_read_b128 v[30:33], v125
	s_waitcnt lgkmcnt(1)
	global_store_dwordx4 v[36:37], v[26:29], off
	s_nop 1
	v_or_b32_e32 v26, v108, v124
	v_lshlrev_b32_e32 v26, 12, v26
	v_mov_b32_e32 v27, v93
	v_lshl_add_u64 v[26:27], v[34:35], 0, v[26:27]
	s_waitcnt lgkmcnt(0)
	global_store_dwordx4 v[26:27], v[30:33], off
	ds_read_b128 v[26:29], v127
	s_nop 0
	v_or_b32_e32 v30, v108, v126
	v_lshlrev_b32_e32 v30, 12, v30
	v_mov_b32_e32 v31, v93
	v_lshl_add_u64 v[36:37], v[34:35], 0, v[30:31]
	ds_read_b128 v[30:33], v129
	s_waitcnt lgkmcnt(1)
	global_store_dwordx4 v[36:37], v[26:29], off
	s_nop 1
	v_or_b32_e32 v26, v108, v128
	v_lshlrev_b32_e32 v26, 12, v26
	v_mov_b32_e32 v27, v93
	v_lshl_add_u64 v[26:27], v[34:35], 0, v[26:27]
	s_waitcnt lgkmcnt(0)
	global_store_dwordx4 v[26:27], v[30:33], off
	ds_read_b128 v[26:29], v131
	s_nop 0
	v_or_b32_e32 v30, v108, v130
	v_lshlrev_b32_e32 v30, 12, v30
	v_mov_b32_e32 v31, v93
	v_lshl_add_u64 v[36:37], v[34:35], 0, v[30:31]
	ds_read_b128 v[30:33], v133
	s_waitcnt lgkmcnt(1)
	global_store_dwordx4 v[36:37], v[26:29], off
	s_nop 1
	v_or_b32_e32 v26, v108, v132
	v_lshlrev_b32_e32 v26, 12, v26
	v_mov_b32_e32 v27, v93
	v_lshl_add_u64 v[26:27], v[34:35], 0, v[26:27]
	s_waitcnt lgkmcnt(0)
	global_store_dwordx4 v[26:27], v[30:33], off
	s_waitcnt lgkmcnt(0)

; __device__ __forceinline__ unsigned pk2(float lo, float hi) { unsigned r; asm volatile("v_cvt_pk_bf16_f32 %0, %1, %2" : "=v"(r) : "v"(lo), "v"(hi)); return r; }
; __device__ __forceinline__ void p0_transpose_item(const float* W, int K, int N, const float* gain, const float* gain2  , bf16_t* WT, LAS unsigned* scr, int item, int lane) {
;     const int nblk = N / 64, kb = item / nblk, nb = item % nblk, k0 = 64 * kb, n0 = 64 * nb;
;     if (gain2 && k0 >= 1024) gain = gain2 - 1024;
;     const int n4 = lane & 15, kq = lane >> 4;
;     f32x4 r0[8], r1[8];
;     const float* src = W + (size_t)(k0 + 2 * kq) * N + n0 + 4 * n4;
; #pragma unroll
;     for (int j = 0; j < 8; ++j) { r0[j] = __builtin_nontemporal_load((const f32x4*)(src + (size_t)(8 * j) * N)); r1[j] = __builtin_nontemporal_load((const f32x4*)(src + (size_t)(8 * j + 1) * N)); }
; #pragma unroll
;     for (int j = 0; j < 8; ++j) {
;         float g0 = 1.f, g1 = 1.f; if (gain) { g0 = gain[k0 + 8 * j + 2 * kq]; g1 = gain[k0 + 8 * j + 2 * kq + 1]; }
; #pragma unroll
;         for (int i = 0; i < 4; ++i) scr[(4 * n4 + i) * 32 + (((j ^ (n4 & 7)) << 2) | kq)] = pk2(r0[j][i] * g0, r1[j][i] * g1);
.Lmy_w164:
	s_andn2_saveexec_b64 s[26:27], s[26:27]
	s_cbranch_execz .Lmy_w117
	v_readlane_b32 s40, v253, 2
	v_mul_i32_i24_e32 v27, 0x6667, v26
	v_readlane_b32 s41, v253, 3
	v_readlane_b32 s42, v253, 4
	v_readlane_b32 s43, v253, 5
	v_readlane_b32 s44, v253, 6
	v_readlane_b32 s45, v253, 7
	v_lshrrev_b32_e32 v30, 31, v27
	v_ashrrev_i32_e32 v27, 20, v27
	v_readlane_b32 s46, v253, 8
	v_readlane_b32 s47, v253, 9
	s_mov_b64 s[40:41], s[44:45]
	v_add_u16_e32 v27, v27, v30
	s_mov_b64 s[42:43], s[46:47]
	v_mul_lo_u16_e32 v30, 40, v27
	v_lshlrev_b32_sdwa v104, v138, sext(v27) dst_sel:DWORD dst_unused:UNUSED_PAD src0_sel:DWORD src1_sel:WORD_0
	v_mov_b64_e32 v[28:29], s[42:43]
	v_sub_u16_e32 v26, v26, v30
	v_or_b32_e32 v108, v104, v91
	v_mad_i64_i32 v[28:29], s[0:1], v100, s64, v[28:29]
	v_lshlrev_b32_sdwa v102, v138, sext(v26) dst_sel:DWORD dst_unused:UNUSED_PAD src0_sel:DWORD src1_sel:WORD_0
	v_mul_hi_i32_i24_e32 v27, 0x2800, v108
	v_mul_i32_i24_e32 v26, 0x2800, v108
	v_lshl_add_u64 v[26:27], v[28:29], 0, v[26:27]
	v_ashrrev_i32_e32 v103, 31, v102
	v_lshl_add_u64 v[26:27], v[102:103], 2, v[26:27]
	v_lshl_add_u64 v[26:27], v[26:27], 0, v[92:93]
	v_add_co_u32_e32 v28, vcc, s37, v26
	s_mov_b32 s0, 0x28000
	s_nop 0
	v_addc_co_u32_e32 v29, vcc, 0, v27, vcc
	global_load_dwordx4 v[82:85], v[26:27], off nt
	global_load_dwordx4 v[86:89], v[28:29], off offset:2048 nt
	v_add_co_u32_e32 v28, vcc, s65, v26
	v_lshlrev_b32_e32 v100, 11, v100
	s_nop 0
	v_addc_co_u32_e32 v29, vcc, 0, v27, vcc
	v_add_co_u32_e32 v30, vcc, s66, v26
	v_ashrrev_i32_e32 v101, 31, v100
	s_nop 0
	v_addc_co_u32_e32 v31, vcc, 0, v27, vcc
	global_load_dwordx4 v[74:77], v[28:29], off nt
	global_load_dwordx4 v[78:81], v[30:31], off offset:2048 nt
	v_add_co_u32_e32 v28, vcc, s0, v26
	v_lshl_add_u64 v[100:101], v[100:101], 2, s[40:41]
	s_nop 0
	v_addc_co_u32_e32 v29, vcc, 0, v27, vcc
	v_add_co_u32_e32 v30, vcc, s67, v26
	v_ashrrev_i32_e32 v109, 31, v108
	s_nop 0
	v_addc_co_u32_e32 v31, vcc, 0, v27, vcc
	global_load_dwordx4 v[66:69], v[28:29], off nt
	global_load_dwordx4 v[70:73], v[30:31], off offset:2048 nt
	v_add_co_u32_e32 v28, vcc, s68, v26
	v_cndmask_b32_e64 v103, 0, 1, s[12:13]
	s_nop 0
	v_addc_co_u32_e32 v29, vcc, 0, v27, vcc
	v_add_co_u32_e32 v30, vcc, s69, v26
	v_mov_b32_e32 v106, 1.0
	s_nop 0
	v_addc_co_u32_e32 v31, vcc, 0, v27, vcc
	global_load_dwordx4 v[58:61], v[28:29], off nt
	global_load_dwordx4 v[62:65], v[30:31], off offset:2048 nt
	v_add_co_u32_e32 v28, vcc, s80, v26
	v_cmp_ne_u32_e64 s[0:1], 1, v103
	s_nop 0
	v_addc_co_u32_e32 v29, vcc, 0, v27, vcc
	v_add_co_u32_e32 v30, vcc, s81, v26
	v_lshl_add_u64 v[100:101], v[108:109], 2, v[100:101]
	s_nop 0
	v_addc_co_u32_e32 v31, vcc, 0, v27, vcc
	global_load_dwordx4 v[50:53], v[28:29], off nt
	s_waitcnt lgkmcnt(0)
	global_load_dwordx4 v[54:57], v[30:31], off offset:2048 nt
	v_add_co_u32_e32 v28, vcc, s70, v26
	v_mov_b32_e32 v108, 1.0
	s_nop 0
	v_addc_co_u32_e32 v29, vcc, 0, v27, vcc
	v_add_co_u32_e32 v30, vcc, s71, v26
	v_mov_b32_e32 v109, 1.0
	s_nop 0
	v_addc_co_u32_e32 v31, vcc, 0, v27, vcc
	global_load_dwordx4 v[42:45], v[28:29], off nt
	global_load_dwordx4 v[46:49], v[30:31], off offset:2048 nt
	v_add_co_u32_e32 v28, vcc, s72, v26
	v_readlane_b32 s48, v253, 10
	s_nop 0
	v_addc_co_u32_e32 v29, vcc, 0, v27, vcc
	v_add_co_u32_e32 v30, vcc, 0x7a000, v26
	v_readlane_b32 s49, v253, 11
	s_nop 0
	v_addc_co_u32_e32 v31, vcc, 0, v27, vcc
	global_load_dwordx4 v[34:37], v[28:29], off nt
	global_load_dwordx4 v[38:41], v[30:31], off offset:2048 nt
	v_add_co_u32_e32 v28, vcc, 0x8c000, v26
	v_readlane_b32 s50, v253, 12
	s_nop 0
	v_addc_co_u32_e32 v29, vcc, 0, v27, vcc
	v_add_co_u32_e32 v30, vcc, 0x8e000, v26
	v_readlane_b32 s51, v253, 13
	s_nop 0
	v_addc_co_u32_e32 v31, vcc, 0, v27, vcc
	global_load_dwordx4 v[26:29], v[28:29], off nt
	s_nop 0
	global_load_dwordx4 v[30:33], v[30:31], off offset:2048 nt
	s_andn2_b64 vcc, exec, s[12:13]
	v_readlane_b32 s52, v253, 14
	v_readlane_b32 s53, v253, 15
	v_readlane_b32 s54, v253, 16
	v_readlane_b32 s55, v253, 17
	s_cbranch_vccnz .Lmy_w167
	global_load_dwordx2 v[108:109], v[100:101], off
.Lmy_w167:
	s_waitcnt vmcnt(0)
	v_mul_f32_e32 v82, v82, v108
	v_mul_f32_e32 v86, v86, v109
	v_cvt_pk_bf16_f32 v82, v82, v86
	v_add_u32_e32 v86, v95, v110
	ds_write_b32 v86, v82
	v_mul_f32_e32 v82, v83, v108
	v_mul_f32_e32 v83, v87, v109
	v_cvt_pk_bf16_f32 v82, v82, v83
	ds_write_b32 v86, v82 offset:128
	v_mul_f32_e32 v82, v84, v108
	v_mul_f32_e32 v83, v88, v109
	v_cvt_pk_bf16_f32 v82, v82, v83
	ds_write_b32 v86, v82 offset:256
	v_mul_f32_e32 v82, v85, v108
	s_and_b64 vcc, exec, s[0:1]
	v_mov_b32_e32 v107, 1.0
	v_mul_f32_e32 v83, v89, v109
	v_cvt_pk_bf16_f32 v82, v82, v83
	ds_write_b32 v86, v82 offset:384
	s_cbranch_vccnz .Lmy_w169
	global_load_dwordx2 v[106:107], v[100:101], off offset:32
.Lmy_w169:
	s_waitcnt vmcnt(0)
	v_mul_f32_e32 v74, v74, v106
	v_mul_f32_e32 v78, v78, v107
	v_cvt_pk_bf16_f32 v74, v74, v78
	v_add_u32_e32 v78, v111, v110
	ds_write_b32 v78, v74
	v_mul_f32_e32 v74, v75, v106
	v_mul_f32_e32 v75, v79, v107
	v_cvt_pk_bf16_f32 v74, v74, v75
	ds_write_b32 v78, v74 offset:128
	v_mul_f32_e32 v74, v76, v106
	v_mul_f32_e32 v75, v80, v107
	v_cvt_pk_bf16_f32 v74, v74, v75
	ds_write_b32 v78, v74 offset:256
	v_mul_f32_e32 v74, v77, v106
	v_mul_f32_e32 v75, v81, v107
	v_cvt_pk_bf16_f32 v74, v74, v75
	ds_write_b32 v78, v74 offset:384
	v_mov_b32_e32 v74, 1.0
	s_and_b64 vcc, exec, s[0:1]
	v_mov_b32_e32 v76, 1.0
	v_mov_b32_e32 v77, 1.0
	s_cbranch_vccnz .Lmy_w171
	global_load_dwordx2 v[76:77], v[100:101], off offset:64
; __device__ __forceinline__ unsigned pk2(float lo, float hi) { unsigned r; asm volatile("v_cvt_pk_bf16_f32 %0, %1, %2" : "=v"(r) : "v"(lo), "v"(hi)); return r; }
; __device__ __forceinline__ void p0_transpose_item(const float* W, int K, int N, const float* gain, const float* gain2  , bf16_t* WT, LAS unsigned* scr, int item, int lane) {
;     ...
;     for (int j = 0; j < 8; ++j) {
;         float g0 = 1.f, g1 = 1.f; if (gain) { g0 = gain[k0 + 8 * j + 2 * kq]; g1 = gain[k0 + 8 * j + 2 * kq + 1]; }
; #pragma unroll
;         for (int i = 0; i < 4; ++i) scr[(4 * n4 + i) * 32 + (((j ^ (n4 & 7)) << 2) | kq)] = pk2(r0[j][i] * g0, r1[j][i] * g1);
;     }
; __device__ __forceinline__ void p0_prologue(const Params& p, LAS unsigned char* lds, int tid) {
;     ...
;     for (int it = gw; it < I_LAYER * DEPTH; it += NGW) {
;         const int l = it / I_LAYER; int r = it % I_LAYER;
;         unsigned char* wl = p.ws + (size_t)l * LAYER_BYTES;
;         if (r < I_IN) { p0_transpose_item(p.in[3] + (size_t)l * DM * INW, DM, INW, p.in[2] + l * DM, nullptr, (bf16_t*)(wl + LO_WIN), scr, r, lane); continue; } r -= I_IN;
;         if (r < I_UP) { p0_transpose_item(p.in[21] + (size_t)l * DM * DFF, DM, DFF, p.in[20] + l * DM, nullptr, (bf16_t*)(wl + LO_WUP), scr, r, lane); continue; } r -= I_UP;
;         if (r < I_DN) { p0_transpose_item(p.in[22] + (size_t)l * DFF * DM, DFF, DM, nullptr, nullptr, (bf16_t*)(wl + LO_WDN), scr, r, lane); continue; } r -= I_DN;
;         if (r < I_GLU) { p0_transpose_item(p.in[15] + (size_t)l * 1024 * 1024, 1024, 1024, nullptr, nullptr, (bf16_t*)(wl + LO_WGLU), scr, r, lane); continue; } r -= I_GLU;
;         p0_transpose_item(p.in[19] + (size_t)l * DM * DM, DM, DM, p.in[17] + l * 1024, p.in[18] + l * 1024, (bf16_t*)(wl + LO_WOUT), scr, r, lane);
;     }
.Lmy_w171:
	s_waitcnt vmcnt(0)
	v_mul_f32_e32 v66, v66, v76
	v_mul_f32_e32 v70, v70, v77
	v_cvt_pk_bf16_f32 v66, v66, v70
	v_add_u32_e32 v70, v112, v110
	ds_write_b32 v70, v66
	v_mul_f32_e32 v66, v67, v76
	v_mul_f32_e32 v67, v71, v77
	v_cvt_pk_bf16_f32 v66, v66, v67
	ds_write_b32 v70, v66 offset:128
	v_mul_f32_e32 v66, v68, v76
	v_mul_f32_e32 v67, v72, v77
	v_cvt_pk_bf16_f32 v66, v66, v67
	ds_write_b32 v70, v66 offset:256
	v_mul_f32_e32 v66, v69, v76
	s_and_b64 vcc, exec, s[0:1]
	v_mov_b32_e32 v75, 1.0
	v_mul_f32_e32 v67, v73, v77
	v_cvt_pk_bf16_f32 v66, v66, v67
	ds_write_b32 v70, v66 offset:384
	s_cbranch_vccnz .Lmy_w173
	global_load_dwordx2 v[74:75], v[100:101], off offset:96
.Lmy_w173:
	s_waitcnt vmcnt(0)
	v_mul_f32_e32 v58, v58, v74
	v_mul_f32_e32 v62, v62, v75
	v_cvt_pk_bf16_f32 v58, v58, v62
	v_add_u32_e32 v62, v113, v110
	ds_write_b32 v62, v58
	v_mul_f32_e32 v58, v59, v74
	v_mul_f32_e32 v59, v63, v75
	v_cvt_pk_bf16_f32 v58, v58, v59
	ds_write_b32 v62, v58 offset:128
	v_mul_f32_e32 v58, v60, v74
	v_mul_f32_e32 v59, v64, v75
	v_cvt_pk_bf16_f32 v58, v58, v59
	ds_write_b32 v62, v58 offset:256
	v_mul_f32_e32 v58, v61, v74
	v_mul_f32_e32 v59, v65, v75
	v_cvt_pk_bf16_f32 v58, v58, v59
	ds_write_b32 v62, v58 offset:384
	v_mov_b32_e32 v58, 1.0
	s_and_b64 vcc, exec, s[0:1]
	v_mov_b32_e32 v60, 1.0
	v_mov_b32_e32 v61, 1.0
	s_cbranch_vccnz .Lmy_w175
	global_load_dwordx2 v[60:61], v[100:101], off offset:128
.Lmy_w175:
	s_waitcnt vmcnt(0)
	v_mul_f32_e32 v50, v50, v60
	v_mul_f32_e32 v54, v54, v61
	v_cvt_pk_bf16_f32 v50, v50, v54
	v_add_u32_e32 v54, v114, v110
	ds_write_b32 v54, v50
	v_mul_f32_e32 v50, v51, v60
	v_mul_f32_e32 v51, v55, v61
	v_cvt_pk_bf16_f32 v50, v50, v51
	ds_write_b32 v54, v50 offset:128
	v_mul_f32_e32 v50, v52, v60
	v_mul_f32_e32 v51, v56, v61
	v_cvt_pk_bf16_f32 v50, v50, v51
	ds_write_b32 v54, v50 offset:256
	v_mul_f32_e32 v50, v53, v60
	s_and_b64 vcc, exec, s[0:1]
	v_mov_b32_e32 v59, 1.0
	v_mul_f32_e32 v51, v57, v61
	v_cvt_pk_bf16_f32 v50, v50, v51
	ds_write_b32 v54, v50 offset:384
	s_cbranch_vccnz .Lmy_w177
	global_load_dwordx2 v[58:59], v[100:101], off offset:160
.Lmy_w177:
	s_waitcnt vmcnt(0)
	v_mul_f32_e32 v42, v42, v58
	v_mul_f32_e32 v46, v46, v59
	v_cvt_pk_bf16_f32 v42, v42, v46
	v_add_u32_e32 v46, v115, v110
	ds_write_b32 v46, v42
	v_mul_f32_e32 v42, v43, v58
	v_mul_f32_e32 v43, v47, v59
	v_cvt_pk_bf16_f32 v42, v42, v43
	ds_write_b32 v46, v42 offset:128
	v_mul_f32_e32 v42, v44, v58
	v_mul_f32_e32 v43, v48, v59
	v_cvt_pk_bf16_f32 v42, v42, v43
	ds_write_b32 v46, v42 offset:256
	v_mul_f32_e32 v42, v45, v58
	v_mul_f32_e32 v43, v49, v59
	v_cvt_pk_bf16_f32 v42, v42, v43
	ds_write_b32 v46, v42 offset:384
	v_mov_b32_e32 v42, 1.0
	s_and_b64 vcc, exec, s[0:1]
	v_mov_b32_e32 v44, 1.0
	v_mov_b32_e32 v45, 1.0
	s_cbranch_vccnz .Lmy_w179
	global_load_dwordx2 v[44:45], v[100:101], off offset:192
.Lmy_w179:
	s_waitcnt vmcnt(0)
	v_mul_f32_e32 v34, v34, v44
	v_mul_f32_e32 v38, v38, v45
	v_cvt_pk_bf16_f32 v34, v34, v38
	v_add_u32_e32 v38, v116, v110
	ds_write_b32 v38, v34
	v_mul_f32_e32 v34, v35, v44
	v_mul_f32_e32 v35, v39, v45
	v_cvt_pk_bf16_f32 v34, v34, v35
	ds_write_b32 v38, v34 offset:128
	v_mul_f32_e32 v34, v36, v44
	v_mul_f32_e32 v35, v40, v45
	v_cvt_pk_bf16_f32 v34, v34, v35
	ds_write_b32 v38, v34 offset:256
	v_mul_f32_e32 v34, v37, v44
	s_and_b64 vcc, exec, s[0:1]
	v_mov_b32_e32 v43, 1.0
	v_mul_f32_e32 v35, v41, v45
	v_cvt_pk_bf16_f32 v34, v34, v35
	ds_write_b32 v38, v34 offset:384
	s_cbranch_vccnz .Lmy_w116
	global_load_dwordx2 v[42:43], v[100:101], off offset:224
	s_branch .Lmy_w116
.Lmy_w181:
	s_or_b64 exec, exec, s[4:5]
	s_waitcnt vmcnt(0) lgkmcnt(0)
	v_readlane_b32 s0, v140, 0
	v_readlane_b32 s1, v140, 1
	v_readlane_b32 s2, v140, 2
	v_readlane_b32 s3, v140, 3
	v_readlane_b32 s4, v140, 4
	v_readlane_b32 s5, v140, 5
	v_readlane_b32 s6, v140, 6
	v_readlane_b32 s7, v140, 7
	v_readlane_b32 s8, v140, 8
	v_readlane_b32 s9, v140, 9
	v_readlane_b32 s10, v140, 10
	v_readlane_b32 s11, v140, 11
	v_readlane_b32 s12, v140, 12
	v_readlane_b32 s13, v140, 13
	v_readlane_b32 s14, v140, 14
	v_readlane_b32 s15, v140, 15
	v_readlane_b32 s16, v140, 16
	v_readlane_b32 s17, v140, 17
	v_readlane_b32 s18, v140, 18
	v_readlane_b32 s19, v140, 19
	v_readlane_b32 s20, v140, 20
	v_readlane_b32 s21, v140, 21
	v_readlane_b32 s22, v140, 22
	v_readlane_b32 s23, v140, 23
	v_readlane_b32 s24, v140, 24
	v_readlane_b32 s25, v140, 25
	v_readlane_b32 s26, v140, 26
	v_readlane_b32 s27, v140, 27
	v_readlane_b32 s28, v140, 28
	v_readlane_b32 s29, v140, 29
	v_readlane_b32 s30, v140, 30
	v_readlane_b32 s31, v140, 31
	v_readlane_b32 s32, v140, 32
	v_readlane_b32 s33, v140, 33
	v_readlane_b32 s34, v140, 34
	v_readlane_b32 s35, v140, 35
	v_readlane_b32 s36, v140, 36
	v_readlane_b32 s37, v140, 37
	v_readlane_b32 s38, v140, 38
	v_readlane_b32 s39, v140, 39
	v_readlane_b32 s40, v140, 40
	v_readlane_b32 s41, v140, 41
	v_readlane_b32 s42, v140, 42
	v_readlane_b32 s43, v140, 43
	v_readlane_b32 s44, v140, 44
	v_readlane_b32 s45, v140, 45
	v_readlane_b32 s46, v140, 46
	v_readlane_b32 s47, v140, 47
	v_readlane_b32 s48, v140, 48
	v_readlane_b32 s49, v140, 49
	v_readlane_b32 s50, v140, 50
	v_readlane_b32 s51, v140, 51
	v_readlane_b32 s52, v140, 52
	v_readlane_b32 s53, v140, 53
	v_readlane_b32 s54, v140, 54
	v_readlane_b32 s55, v140, 55
	v_readlane_b32 s56, v140, 56
	v_readlane_b32 s57, v140, 57
	v_readlane_b32 s58, v140, 58
	v_readlane_b32 s59, v140, 59
	v_readlane_b32 s60, v140, 60
	v_readlane_b32 s61, v140, 61
	v_readlane_b32 s62, v140, 62
	v_readlane_b32 s63, v140, 63
	v_readlane_b32 s64, v141, 0
	v_readlane_b32 s65, v141, 1
	v_readlane_b32 s66, v141, 2
	v_readlane_b32 s67, v141, 3
	v_readlane_b32 s68, v141, 4
	v_readlane_b32 s69, v141, 5
	v_readlane_b32 s70, v141, 6
	v_readlane_b32 s71, v141, 7
	v_readlane_b32 s72, v141, 8
	v_readlane_b32 s73, v141, 9
	v_readlane_b32 s74, v141, 10
	v_readlane_b32 s75, v141, 11
	v_readlane_b32 s76, v141, 12
	v_readlane_b32 s77, v141, 13
	v_readlane_b32 s78, v141, 14
	v_readlane_b32 s79, v141, 15
	v_readlane_b32 s80, v141, 16
	v_readlane_b32 s81, v141, 17
	v_readlane_b32 s82, v141, 18
	v_readlane_b32 s83, v141, 19
	v_readlane_b32 s84, v141, 20
	v_readlane_b32 s85, v141, 21
	v_readlane_b32 s86, v141, 22
	v_readlane_b32 s87, v141, 23
	v_readlane_b32 s88, v141, 24
	v_readlane_b32 s89, v141, 25
	v_readlane_b32 s90, v141, 26
	v_readlane_b32 s91, v141, 27
	v_readlane_b32 s92, v141, 28
	v_readlane_b32 s93, v141, 29
	v_readlane_b32 s94, v141, 30
	v_readlane_b32 s95, v141, 31
	v_readlane_b32 s96, v141, 32
	v_readlane_b32 s97, v141, 33
	s_nop 4
	s_branch .Lmy_w_skip

; #define LAS __attribute__((address_space(3)))
; __device__ __forceinline__ void p0_prologue(const Params& p, LAS unsigned char* lds, int tid) {
;     ...
;     LAS unsigned* scr = (LAS unsigned*)(lds + wave * 8192);
;     const int gw = blockIdx.x * 8 + wave, NGW = gridDim.x * 8;
;     ...
;     for (int it = gw; it < I_LAYER * DEPTH; it += NGW) {
;         const int l = it / I_LAYER; int r = it % I_LAYER;
;         unsigned char* wl = p.ws + (size_t)l * LAYER_BYTES;
.LBB0_427:
	v_readlane_b32 s98, v254, 36
	v_readlane_b32 s99, v253, 34
	s_cmp_gt_u32 s98, 2
	s_cbranch_scc1 .Lmy_w_skip
	s_cmp_lt_u32 s99, 64
	s_cbranch_scc1 .Lmy_w_skip
	v_writelane_b32 v140, s0, 0
	v_writelane_b32 v140, s1, 1
	v_writelane_b32 v140, s2, 2
	v_writelane_b32 v140, s3, 3
	v_writelane_b32 v140, s4, 4
	v_writelane_b32 v140, s5, 5
	v_writelane_b32 v140, s6, 6
	v_writelane_b32 v140, s7, 7
	v_writelane_b32 v140, s8, 8
	v_writelane_b32 v140, s9, 9
	v_writelane_b32 v140, s10, 10
	v_writelane_b32 v140, s11, 11
	v_writelane_b32 v140, s12, 12
	v_writelane_b32 v140, s13, 13
	v_writelane_b32 v140, s14, 14
	v_writelane_b32 v140, s15, 15
	v_writelane_b32 v140, s16, 16
	v_writelane_b32 v140, s17, 17
	v_writelane_b32 v140, s18, 18
	v_writelane_b32 v140, s19, 19
	v_writelane_b32 v140, s20, 20
	v_writelane_b32 v140, s21, 21
	v_writelane_b32 v140, s22, 22
	v_writelane_b32 v140, s23, 23
	v_writelane_b32 v140, s24, 24
	v_writelane_b32 v140, s25, 25
	v_writelane_b32 v140, s26, 26
	v_writelane_b32 v140, s27, 27
	v_writelane_b32 v140, s28, 28
	v_writelane_b32 v140, s29, 29
	v_writelane_b32 v140, s30, 30
	v_writelane_b32 v140, s31, 31
	v_writelane_b32 v140, s32, 32
	v_writelane_b32 v140, s33, 33
	v_writelane_b32 v140, s34, 34
	v_writelane_b32 v140, s35, 35
	v_writelane_b32 v140, s36, 36
	v_writelane_b32 v140, s37, 37
	v_writelane_b32 v140, s38, 38
	v_writelane_b32 v140, s39, 39
	v_writelane_b32 v140, s40, 40
	v_writelane_b32 v140, s41, 41
	v_writelane_b32 v140, s42, 42
	v_writelane_b32 v140, s43, 43
	v_writelane_b32 v140, s44, 44
	v_writelane_b32 v140, s45, 45
	v_writelane_b32 v140, s46, 46
	v_writelane_b32 v140, s47, 47
	v_writelane_b32 v140, s48, 48
	v_writelane_b32 v140, s49, 49
	v_writelane_b32 v140, s50, 50
	v_writelane_b32 v140, s51, 51
	v_writelane_b32 v140, s52, 52
	v_writelane_b32 v140, s53, 53
	v_writelane_b32 v140, s54, 54
	v_writelane_b32 v140, s55, 55
	v_writelane_b32 v140, s56, 56
	v_writelane_b32 v140, s57, 57
	v_writelane_b32 v140, s58, 58
	v_writelane_b32 v140, s59, 59
	v_writelane_b32 v140, s60, 60
	v_writelane_b32 v140, s61, 61
	v_writelane_b32 v140, s62, 62
	v_writelane_b32 v140, s63, 63
	v_writelane_b32 v141, s64, 0
	v_writelane_b32 v141, s65, 1
	v_writelane_b32 v141, s66, 2
	v_writelane_b32 v141, s67, 3
	v_writelane_b32 v141, s68, 4
	v_writelane_b32 v141, s69, 5
	v_writelane_b32 v141, s70, 6
	v_writelane_b32 v141, s71, 7
	v_writelane_b32 v141, s72, 8
	v_writelane_b32 v141, s73, 9
	v_writelane_b32 v141, s74, 10
	v_writelane_b32 v141, s75, 11
	v_writelane_b32 v141, s76, 12
	v_writelane_b32 v141, s77, 13
	v_writelane_b32 v141, s78, 14
	v_writelane_b32 v141, s79, 15
	v_writelane_b32 v141, s80, 16
	v_writelane_b32 v141, s81, 17
	v_writelane_b32 v141, s82, 18
	v_writelane_b32 v141, s83, 19
	v_writelane_b32 v141, s84, 20
	v_writelane_b32 v141, s85, 21
	v_writelane_b32 v141, s86, 22
	v_writelane_b32 v141, s87, 23
	v_writelane_b32 v141, s88, 24
	v_writelane_b32 v141, s89, 25
	v_writelane_b32 v141, s90, 26
	v_writelane_b32 v141, s91, 27
	v_writelane_b32 v141, s92, 28
	v_writelane_b32 v141, s93, 29
	v_writelane_b32 v141, s94, 30
	v_writelane_b32 v141, s95, 31
	v_writelane_b32 v141, s96, 32
	v_writelane_b32 v141, s97, 33
	s_add_i32 s98, s98, 2
	s_mul_i32 s98, s98, 0x2a00
	s_add_i32 s0, s98, 0xffffd600
	s_sub_i32 s1, s99, 64
	s_lshl_b32 s1, s1, 3
	s_add_i32 s0, s0, s1
	v_and_b32_e32 v34, 63, v201
	v_lshrrev_b32_e32 v35, 6, v201
	v_lshlrev_b32_e32 v36, 3, v201
	v_add_u32_e32 v90, s0, v35
	s_add_i32 s99, s98, -1
	s_movk_i32 s10, 0x600
	v_readlane_b32 s62, v255, 8
	v_readlane_b32 s63, v255, 9
	s_branch .Lmy_w_entry
